# v85 + GEMM tiles: no accumulator zeroing; first half of the first K iteration issued from a copy whose first-touch MFMAs take C=0, joining the loop at K-tile 1
# speedup vs baseline: 1.0263x; 1.0061x over previous
; #define PG8_STAGE(bufoff, gbase, voff) do { _Pragma("unroll") for (int _i = 0; _i < 2; ++_i) \
;         __builtin_amdgcn_global_load_lds((const unsigned*)((const char*)(gbase) + (voff)[_i]), (PG8_LAS unsigned*)(lds + (bufoff) + ldsw + _i * 8192), 16, 0, 0); } while (0)
; #define PG8_LDA(dst, b, h) do { _Pragma("unroll") for (int m = 0; m < 4; ++m) _Pragma("unroll") for (int k = 0; k < 2; ++k) dst[m][k] = *(const PG8_LAS bf16x8*)(lds + PG8_SA(b, h) + aoff + m * 2048 + k * 1024); } while (0)
; #define PG8_LDB(dst, b, h) do { _Pragma("unroll") for (int n = 0; n < 2; ++n) _Pragma("unroll") for (int k = 0; k < 2; ++k) dst[n][k] = *(const PG8_LAS bf16x8*)(lds + PG8_SB(b, h) + boff + n * 2048 + k * 1024); } while (0)
; #define PG8_MMA(ai, bj, At, Bt) do { __builtin_amdgcn_s_setprio(1); _Pragma("unroll") for (int m = 0; m < 4; ++m) _Pragma("unroll") for (int n = 0; n < 2; ++n) _Pragma("unroll") for (int k = 0; k < 2; ++k) \
;         acc[ai][bj][m][n] = __builtin_amdgcn_mfma_f32_16x16x32_bf16(Bt[n][k], At[m][k], acc[ai][bj][m][n], 0, 0, 0); __builtin_amdgcn_s_setprio(0); } while (0)
; #define PG8_WAIT_V(n) asm volatile("s_waitcnt vmcnt(" #n ")" ::: "memory")
; #define PG8_WAIT_L(n) asm volatile("s_waitcnt lgkmcnt(" #n ")" ::: "memory")
; #define PG8_BAR __builtin_amdgcn_s_barrier()
; #define PG8_SCHED __builtin_amdgcn_sched_barrier(0)
; template <class Epi, class Sched, bool ALIGN_EPI = false, bool SP2 = false>
; __device__ __forceinline__ void gemm_phase(PG8_LAS unsigned char* lds, const Gemm g, const Sched& S, const Epi& E) {
;     ...
;         for (int t = 0; t < nt; t += 2) {
;             const bool last = (t == nt - 2);
;             const char* a1 = cA + (size_t)(t + 1) * kstep;
;             const char* a2 = last ? nA : cA + (size_t)(t + 2) * kstep; const char* b2 = last ? nB : cB + (size_t)(t + 2) * kstep;
;             const char* a3 = a2 + kstep; const char* b3 = b2 + kstep;
;             if (last && has_next) S.a_ready(nxt);
;             if constexpr (SP2) {
;             PG8_LDB(B0, 0, 0); PG8_LDB(B1, 0, 1); PG8_SCHED; PG8_LDA(At, 0, 0); PG8_STAGE(PG8_SA(1, 1), a1 + hstep, voffA);
;             PG8_WAIT_V(8); PG8_WAIT_L(0); PG8_BAR; PG8_MMA(0, 0, At, B0); PG8_MMA(0, 1, At, B1); PG8_BAR; PG8_SCHED;
.LBB0_99:
	s_ashr_i32 s21, s20, 31
	s_lshl_b64 s[24:25], s[20:21], 19
	s_add_u32 s24, s35, s24
	s_addc_u32 s25, s38, s25
	s_and_b64 s[26:27], s[4:5], exec
	s_cselect_b32 s3, s25, s9
	s_cselect_b32 s7, s24, s8
	s_ashr_i32 s23, s22, 31
	s_lshl_b64 s[26:27], s[22:23], 19
	s_add_u32 s26, s39, s26
	s_addc_u32 s27, s40, s27
	s_and_b64 s[30:31], s[4:5], exec
	s_cselect_b32 s11, s27, s29
	s_cselect_b32 s21, s26, s28
	s_add_u32 s8, s8, 0x40080
	s_addc_u32 s9, s9, 0
	s_add_u32 s23, s28, 0x100
	s_addc_u32 s44, s29, 0
	s_mov_b32 s45, -2
	s_add_u32 s28, s8, 0xfffc0080
	s_addc_u32 s29, s9, -1
	s_cmp_eq_u32 s45, 12
	s_cselect_b32 s31, s3, s29
	s_cselect_b32 s30, s7, s28
	s_cselect_b32 s29, s11, s44
	s_cselect_b32 s28, s21, s23
	ds_read_b128 v[132:135], v204
	ds_read_b128 v[136:139], v204 offset:1024
	ds_read_b128 v[140:143], v204 offset:2048
	ds_read_b128 v[144:147], v204 offset:3072
	ds_read_b128 v[148:151], v204 offset:16384
	ds_read_b128 v[152:155], v204 offset:17408
	ds_read_b128 v[156:159], v204 offset:18432
	ds_read_b128 v[160:163], v204 offset:19456
	v_lshl_add_u64 v[194:195], s[8:9], 0, v[178:179]
	s_add_i32 m0, s42, 0xc000
	ds_read_b128 v[164:167], v205
	ds_read_b128 v[182:185], v205 offset:1024
	ds_read_b128 v[186:189], v205 offset:2048
	ds_read_b128 v[190:193], v205 offset:3072
	ds_read_b128 v[208:211], v205 offset:4096
	ds_read_b128 v[212:215], v205 offset:5120
	ds_read_b128 v[216:219], v205 offset:6144
	ds_read_b128 v[220:223], v205 offset:7168
	global_load_lds_dwordx4 v[194:195], off
	s_add_i32 m0, s42, 0xe000
	v_lshl_add_u64 v[194:195], s[8:9], 0, v[180:181]
	global_load_lds_dwordx4 v[194:195], off
	s_waitcnt vmcnt(8) lgkmcnt(0)
	s_barrier
	s_setprio 1
	v_mfma_f32_16x16x32_bf16 v[128:131], v[132:135], v[164:167], 0
	v_mfma_f32_16x16x32_bf16 v[124:127], v[140:143], v[164:167], 0
	v_mfma_f32_16x16x32_bf16 v[112:115], v[132:135], v[186:189], 0
	v_mfma_f32_16x16x32_bf16 v[108:111], v[140:143], v[186:189], 0
	v_mfma_f32_16x16x32_bf16 v[96:99], v[132:135], v[208:211], 0
	v_mfma_f32_16x16x32_bf16 v[92:95], v[140:143], v[208:211], 0
	v_mfma_f32_16x16x32_bf16 v[80:83], v[132:135], v[216:219], 0
	v_mfma_f32_16x16x32_bf16 v[76:79], v[140:143], v[216:219], 0
	v_mfma_f32_16x16x32_bf16 v[128:131], v[136:139], v[182:185], v[128:131]
	v_mfma_f32_16x16x32_bf16 v[124:127], v[144:147], v[182:185], v[124:127]
	v_mfma_f32_16x16x32_bf16 v[112:115], v[136:139], v[190:193], v[112:115]
	v_mfma_f32_16x16x32_bf16 v[108:111], v[144:147], v[190:193], v[108:111]
	v_mfma_f32_16x16x32_bf16 v[96:99], v[136:139], v[212:215], v[96:99]
	v_mfma_f32_16x16x32_bf16 v[92:95], v[144:147], v[212:215], v[92:95]
	v_mfma_f32_16x16x32_bf16 v[80:83], v[136:139], v[220:223], v[80:83]
	v_mfma_f32_16x16x32_bf16 v[76:79], v[144:147], v[220:223], v[76:79]
	s_setprio 0
	s_setprio 1
	v_mfma_f32_16x16x32_bf16 v[120:123], v[148:151], v[164:167], 0
	v_mfma_f32_16x16x32_bf16 v[116:119], v[156:159], v[164:167], 0
	v_mfma_f32_16x16x32_bf16 v[104:107], v[148:151], v[186:189], 0
	v_mfma_f32_16x16x32_bf16 v[100:103], v[156:159], v[186:189], 0
	v_mfma_f32_16x16x32_bf16 v[88:91], v[148:151], v[208:211], 0
	v_mfma_f32_16x16x32_bf16 v[84:87], v[156:159], v[208:211], 0
	v_mfma_f32_16x16x32_bf16 v[72:75], v[148:151], v[216:219], 0
	v_mfma_f32_16x16x32_bf16 v[68:71], v[156:159], v[216:219], 0
	v_mfma_f32_16x16x32_bf16 v[120:123], v[152:155], v[182:185], v[120:123]
	v_mfma_f32_16x16x32_bf16 v[116:119], v[160:163], v[182:185], v[116:119]
	v_mfma_f32_16x16x32_bf16 v[104:107], v[152:155], v[190:193], v[104:107]
	v_mfma_f32_16x16x32_bf16 v[100:103], v[160:163], v[190:193], v[100:103]
	v_mfma_f32_16x16x32_bf16 v[88:91], v[152:155], v[212:215], v[88:91]
	v_mfma_f32_16x16x32_bf16 v[84:87], v[160:163], v[212:215], v[84:87]
	v_mfma_f32_16x16x32_bf16 v[72:75], v[152:155], v[220:223], v[72:75]
	v_mfma_f32_16x16x32_bf16 v[68:71], v[160:163], v[220:223], v[68:71]
	s_setprio 0
	s_barrier
; #define PG8_STAGE(bufoff, gbase, voff) do { _Pragma("unroll") for (int _i = 0; _i < 2; ++_i) \
;         __builtin_amdgcn_global_load_lds((const unsigned*)((const char*)(gbase) + (voff)[_i]), (PG8_LAS unsigned*)(lds + (bufoff) + ldsw + _i * 8192), 16, 0, 0); } while (0)
; #define PG8_LDA(dst, b, h) do { _Pragma("unroll") for (int m = 0; m < 4; ++m) _Pragma("unroll") for (int k = 0; k < 2; ++k) dst[m][k] = *(const PG8_LAS bf16x8*)(lds + PG8_SA(b, h) + aoff + m * 2048 + k * 1024); } while (0)
; #define PG8_MMA(ai, bj, At, Bt) do { __builtin_amdgcn_s_setprio(1); _Pragma("unroll") for (int m = 0; m < 4; ++m) _Pragma("unroll") for (int n = 0; n < 2; ++n) _Pragma("unroll") for (int k = 0; k < 2; ++k) \
;         acc[ai][bj][m][n] = __builtin_amdgcn_mfma_f32_16x16x32_bf16(Bt[n][k], At[m][k], acc[ai][bj][m][n], 0, 0, 0); __builtin_amdgcn_s_setprio(0); } while (0)
; #define PG8_WAIT_V(n) asm volatile("s_waitcnt vmcnt(" #n ")" ::: "memory")
; #define PG8_WAIT_L(n) asm volatile("s_waitcnt lgkmcnt(" #n ")" ::: "memory")
; #define PG8_BAR __builtin_amdgcn_s_barrier()
; #define PG8_SCHED __builtin_amdgcn_sched_barrier(0)
; template <class Epi, class Sched, bool ALIGN_EPI = false, bool SP2 = false>
; __device__ __forceinline__ void gemm_phase(PG8_LAS unsigned char* lds, const Gemm g, const Sched& S, const Epi& E) {
;     ...
;             PG8_LDA(At, 0, 1); PG8_STAGE(PG8_SB(0, 0), b2, voffB); PG8_STAGE(PG8_SB(0, 1), b2 + hstep, voffB); PG8_STAGE(PG8_SA(0, 0), a2, voffA);
;             PG8_WAIT_V(8); PG8_WAIT_L(0); PG8_BAR; PG8_MMA(1, 0, At, B0); PG8_MMA(1, 1, At, B1); PG8_BAR; PG8_SCHED;
	v_lshl_add_u64 v[194:195], s[28:29], 0, v[168:169]
	s_add_i32 m0, s41, 0x10000
	ds_read_b128 v[164:167], v205 offset:16384
	ds_read_b128 v[182:185], v205 offset:17408
	ds_read_b128 v[186:189], v205 offset:18432
	ds_read_b128 v[190:193], v205 offset:19456
	ds_read_b128 v[208:211], v205 offset:20480
	ds_read_b128 v[212:215], v205 offset:21504
	ds_read_b128 v[216:219], v205 offset:22528
	ds_read_b128 v[220:223], v205 offset:23552
	global_load_lds_dwordx4 v[194:195], off
	s_add_i32 m0, s41, 0x12000
	s_add_u32 s54, s28, 0x40000
	v_lshl_add_u64 v[202:203], s[28:29], 0, v[172:173]
	s_addc_u32 s55, s29, 0
	global_load_lds_dwordx4 v[202:203], off
	v_lshl_add_u64 v[224:225], s[54:55], 0, v[168:169]
	s_add_i32 m0, s41, 0x14000
	v_lshl_add_u64 v[226:227], s[30:31], 0, v[170:171]
	global_load_lds_dwordx4 v[224:225], off
	s_add_i32 m0, s41, 0x16000
	v_lshl_add_u64 v[224:225], s[54:55], 0, v[172:173]
	global_load_lds_dwordx4 v[224:225], off
	s_mov_b32 m0, s42
	v_lshl_add_u64 v[224:225], s[30:31], 0, v[0:1]
	global_load_lds_dwordx4 v[224:225], off
	s_mov_b32 m0, s43
	s_add_i32 s53, 0, 0x18000
	global_load_lds_dwordx4 v[226:227], off
	s_waitcnt vmcnt(8) lgkmcnt(0)
	s_barrier
	s_setprio 1
	v_mfma_f32_16x16x32_bf16 v[64:67], v[132:135], v[164:167], 0
	v_mfma_f32_16x16x32_bf16 v[60:63], v[140:143], v[164:167], 0
	v_mfma_f32_16x16x32_bf16 v[48:51], v[132:135], v[186:189], 0
	v_mfma_f32_16x16x32_bf16 v[44:47], v[140:143], v[186:189], 0
	v_mfma_f32_16x16x32_bf16 v[32:35], v[132:135], v[208:211], 0
	v_mfma_f32_16x16x32_bf16 v[28:31], v[140:143], v[208:211], 0
	v_mfma_f32_16x16x32_bf16 v[16:19], v[132:135], v[216:219], 0
	v_mfma_f32_16x16x32_bf16 v[12:15], v[140:143], v[216:219], 0
	v_mfma_f32_16x16x32_bf16 v[64:67], v[136:139], v[182:185], v[64:67]
	v_mfma_f32_16x16x32_bf16 v[60:63], v[144:147], v[182:185], v[60:63]
	v_mfma_f32_16x16x32_bf16 v[48:51], v[136:139], v[190:193], v[48:51]
	v_mfma_f32_16x16x32_bf16 v[44:47], v[144:147], v[190:193], v[44:47]
	v_mfma_f32_16x16x32_bf16 v[32:35], v[136:139], v[212:215], v[32:35]
	v_mfma_f32_16x16x32_bf16 v[28:31], v[144:147], v[212:215], v[28:31]
	v_mfma_f32_16x16x32_bf16 v[16:19], v[136:139], v[220:223], v[16:19]
	v_mfma_f32_16x16x32_bf16 v[12:15], v[144:147], v[220:223], v[12:15]
	s_setprio 0
	s_setprio 1
	v_mfma_f32_16x16x32_bf16 v[56:59], v[148:151], v[164:167], 0
	v_mfma_f32_16x16x32_bf16 v[52:55], v[156:159], v[164:167], 0
	v_mfma_f32_16x16x32_bf16 v[40:43], v[148:151], v[186:189], 0
	v_mfma_f32_16x16x32_bf16 v[36:39], v[156:159], v[186:189], 0
	v_mfma_f32_16x16x32_bf16 v[24:27], v[148:151], v[208:211], 0
	v_mfma_f32_16x16x32_bf16 v[20:23], v[156:159], v[208:211], 0
	v_mfma_f32_16x16x32_bf16 v[8:11], v[148:151], v[216:219], 0
	v_mfma_f32_16x16x32_bf16 v[4:7], v[156:159], v[216:219], 0
	v_mfma_f32_16x16x32_bf16 v[56:59], v[152:155], v[182:185], v[56:59]
	v_mfma_f32_16x16x32_bf16 v[52:55], v[160:163], v[182:185], v[52:55]
	v_mfma_f32_16x16x32_bf16 v[40:43], v[152:155], v[190:193], v[40:43]
	v_mfma_f32_16x16x32_bf16 v[36:39], v[160:163], v[190:193], v[36:39]
	v_mfma_f32_16x16x32_bf16 v[24:27], v[152:155], v[212:215], v[24:27]
	v_mfma_f32_16x16x32_bf16 v[20:23], v[160:163], v[212:215], v[20:23]
	v_mfma_f32_16x16x32_bf16 v[8:11], v[152:155], v[220:223], v[8:11]
	v_mfma_f32_16x16x32_bf16 v[4:7], v[160:163], v[220:223], v[4:7]
	s_setprio 0
	s_barrier
	s_branch .Lkmid_0

; #define PG8_STAGE(bufoff, gbase, voff) do { _Pragma("unroll") for (int _i = 0; _i < 2; ++_i) \
;         __builtin_amdgcn_global_load_lds((const unsigned*)((const char*)(gbase) + (voff)[_i]), (PG8_LAS unsigned*)(lds + (bufoff) + ldsw + _i * 8192), 16, 0, 0); } while (0)
; #define PG8_LDA(dst, b, h) do { _Pragma("unroll") for (int m = 0; m < 4; ++m) _Pragma("unroll") for (int k = 0; k < 2; ++k) dst[m][k] = *(const PG8_LAS bf16x8*)(lds + PG8_SA(b, h) + aoff + m * 2048 + k * 1024); } while (0)
; #define PG8_LDB(dst, b, h) do { _Pragma("unroll") for (int n = 0; n < 2; ++n) _Pragma("unroll") for (int k = 0; k < 2; ++k) dst[n][k] = *(const PG8_LAS bf16x8*)(lds + PG8_SB(b, h) + boff + n * 2048 + k * 1024); } while (0)
; #define PG8_MMA(ai, bj, At, Bt) do { __builtin_amdgcn_s_setprio(1); _Pragma("unroll") for (int m = 0; m < 4; ++m) _Pragma("unroll") for (int n = 0; n < 2; ++n) _Pragma("unroll") for (int k = 0; k < 2; ++k) \
;         acc[ai][bj][m][n] = __builtin_amdgcn_mfma_f32_16x16x32_bf16(Bt[n][k], At[m][k], acc[ai][bj][m][n], 0, 0, 0); __builtin_amdgcn_s_setprio(0); } while (0)
; #define PG8_WAIT_V(n) asm volatile("s_waitcnt vmcnt(" #n ")" ::: "memory")
; #define PG8_WAIT_L(n) asm volatile("s_waitcnt lgkmcnt(" #n ")" ::: "memory")
; #define PG8_BAR __builtin_amdgcn_s_barrier()
; #define PG8_SCHED __builtin_amdgcn_sched_barrier(0)
; template <class Epi, class Sched, bool ALIGN_EPI = false, bool SP2 = false>
; __device__ __forceinline__ void gemm_phase(PG8_LAS unsigned char* lds, const Gemm g, const Sched& S, const Epi& E) {
;     ...
;             PG8_LDB(B0, 1, 0); PG8_LDB(B1, 1, 1); PG8_SCHED; PG8_LDA(At, 1, 0); PG8_STAGE(PG8_SA(0, 1), a2 + hstep, voffA);
;             PG8_WAIT_V(8); PG8_WAIT_L(0); PG8_BAR; PG8_MMA(0, 0, At, B0); PG8_MMA(0, 1, At, B1); PG8_BAR; PG8_SCHED;
;             PG8_LDA(At, 1, 1); PG8_STAGE(PG8_SB(1, 0), b3, voffB); PG8_STAGE(PG8_SB(1, 1), b3 + hstep, voffB); PG8_STAGE(PG8_SA(1, 0), a3, voffA);
;             PG8_WAIT_V(8); PG8_WAIT_L(0); PG8_BAR; PG8_MMA(1, 0, At, B0); PG8_MMA(1, 1, At, B1); PG8_BAR; PG8_SCHED;
.Lkmid_0:
	ds_read_b128 v[132:135], v204 offset:32768
	ds_read_b128 v[136:139], v204 offset:33792
	ds_read_b128 v[140:143], v204 offset:34816
	ds_read_b128 v[144:147], v204 offset:35840
	ds_read_b128 v[148:151], v204 offset:49152
	ds_read_b128 v[152:155], v204 offset:50176
	ds_read_b128 v[156:159], v204 offset:51200
	ds_read_b128 v[160:163], v204 offset:52224
	s_add_u32 s30, s30, 0x40000
	s_addc_u32 s31, s31, 0
	s_mov_b32 m0, s46
	v_lshl_add_u64 v[228:229], s[30:31], 0, v[0:1]
	ds_read_b128 v[164:167], v205 offset:32768
	ds_read_b128 v[182:185], v205 offset:33792
	ds_read_b128 v[186:189], v205 offset:34816
	ds_read_b128 v[190:193], v205 offset:35840
	ds_read_b128 v[208:211], v205 offset:36864
	ds_read_b128 v[212:215], v205 offset:37888
	ds_read_b128 v[216:219], v205 offset:38912
	ds_read_b128 v[220:223], v205 offset:39936
	global_load_lds_dwordx4 v[228:229], off
	s_mov_b32 m0, s47
	v_lshl_add_u64 v[228:229], s[30:31], 0, v[170:171]
	global_load_lds_dwordx4 v[228:229], off
	s_waitcnt vmcnt(8) lgkmcnt(0)
	s_barrier
	s_setprio 1
	v_mfma_f32_16x16x32_bf16 v[128:131], v[132:135], v[164:167], v[128:131]
	v_mfma_f32_16x16x32_bf16 v[124:127], v[140:143], v[164:167], v[124:127]
	v_mfma_f32_16x16x32_bf16 v[112:115], v[132:135], v[186:189], v[112:115]
	v_mfma_f32_16x16x32_bf16 v[108:111], v[140:143], v[186:189], v[108:111]
	v_mfma_f32_16x16x32_bf16 v[96:99], v[132:135], v[208:211], v[96:99]
	v_mfma_f32_16x16x32_bf16 v[92:95], v[140:143], v[208:211], v[92:95]
	v_mfma_f32_16x16x32_bf16 v[80:83], v[132:135], v[216:219], v[80:83]
	v_mfma_f32_16x16x32_bf16 v[76:79], v[140:143], v[216:219], v[76:79]
	v_mfma_f32_16x16x32_bf16 v[128:131], v[136:139], v[182:185], v[128:131]
	v_mfma_f32_16x16x32_bf16 v[124:127], v[144:147], v[182:185], v[124:127]
	v_mfma_f32_16x16x32_bf16 v[112:115], v[136:139], v[190:193], v[112:115]
	v_mfma_f32_16x16x32_bf16 v[108:111], v[144:147], v[190:193], v[108:111]
	v_mfma_f32_16x16x32_bf16 v[96:99], v[136:139], v[212:215], v[96:99]
	v_mfma_f32_16x16x32_bf16 v[92:95], v[144:147], v[212:215], v[92:95]
	v_mfma_f32_16x16x32_bf16 v[80:83], v[136:139], v[220:223], v[80:83]
	v_mfma_f32_16x16x32_bf16 v[76:79], v[144:147], v[220:223], v[76:79]
	s_setprio 0
	s_setprio 1
	v_mfma_f32_16x16x32_bf16 v[120:123], v[148:151], v[164:167], v[120:123]
	v_mfma_f32_16x16x32_bf16 v[116:119], v[156:159], v[164:167], v[116:119]
	v_mfma_f32_16x16x32_bf16 v[104:107], v[148:151], v[186:189], v[104:107]
	v_mfma_f32_16x16x32_bf16 v[100:103], v[156:159], v[186:189], v[100:103]
	v_mfma_f32_16x16x32_bf16 v[88:91], v[148:151], v[208:211], v[88:91]
	v_mfma_f32_16x16x32_bf16 v[84:87], v[156:159], v[208:211], v[84:87]
	v_mfma_f32_16x16x32_bf16 v[72:75], v[148:151], v[216:219], v[72:75]
	v_mfma_f32_16x16x32_bf16 v[68:71], v[156:159], v[216:219], v[68:71]
	v_mfma_f32_16x16x32_bf16 v[120:123], v[152:155], v[182:185], v[120:123]
	v_mfma_f32_16x16x32_bf16 v[116:119], v[160:163], v[182:185], v[116:119]
	v_mfma_f32_16x16x32_bf16 v[104:107], v[152:155], v[190:193], v[104:107]
	v_mfma_f32_16x16x32_bf16 v[100:103], v[160:163], v[190:193], v[100:103]
	v_mfma_f32_16x16x32_bf16 v[88:91], v[152:155], v[212:215], v[88:91]
	v_mfma_f32_16x16x32_bf16 v[84:87], v[160:163], v[212:215], v[84:87]
	v_mfma_f32_16x16x32_bf16 v[72:75], v[152:155], v[220:223], v[72:75]
	v_mfma_f32_16x16x32_bf16 v[68:71], v[160:163], v[220:223], v[68:71]
	s_setprio 0
	s_barrier
	s_add_i32 m0, s41, 0x17f80
	ds_read_b128 v[164:167], v205 offset:49152
	ds_read_b128 v[182:185], v205 offset:50176
	ds_read_b128 v[186:189], v205 offset:51200
	ds_read_b128 v[190:193], v205 offset:52224
	ds_read_b128 v[208:211], v205 offset:53248
	ds_read_b128 v[212:215], v205 offset:54272
	ds_read_b128 v[216:219], v205 offset:55296
	ds_read_b128 v[220:223], v205 offset:56320
	global_load_lds_dwordx4 v[194:195], off offset:128
	s_add_i32 m0, s41, 0x19f80
	s_add_u32 s28, s28, 0x40080
	s_addc_u32 s29, s29, 0
	global_load_lds_dwordx4 v[202:203], off offset:128
	s_add_i32 m0, s41, 0x1c000
	v_lshl_add_u64 v[194:195], s[28:29], 0, v[168:169]
	global_load_lds_dwordx4 v[194:195], off
	s_add_i32 m0, s41, 0x1e000
	v_lshl_add_u64 v[194:195], s[28:29], 0, v[172:173]
	global_load_lds_dwordx4 v[194:195], off
	s_add_i32 m0, s50, 0xffffff80
	s_add_u32 s8, s8, 0x100
	s_addc_u32 s9, s9, 0
	global_load_lds_dwordx4 v[224:225], off offset:128
	s_add_i32 m0, s51, 0xffffff80
	s_add_u32 s23, s23, 0x100
	s_addc_u32 s44, s44, 0
	global_load_lds_dwordx4 v[226:227], off offset:128
	s_waitcnt vmcnt(8) lgkmcnt(0)
	s_barrier
	s_setprio 1
	v_mfma_f32_16x16x32_bf16 v[64:67], v[132:135], v[164:167], v[64:67]
	v_mfma_f32_16x16x32_bf16 v[60:63], v[140:143], v[164:167], v[60:63]
	v_mfma_f32_16x16x32_bf16 v[48:51], v[132:135], v[186:189], v[48:51]
	v_mfma_f32_16x16x32_bf16 v[44:47], v[140:143], v[186:189], v[44:47]
	v_mfma_f32_16x16x32_bf16 v[32:35], v[132:135], v[208:211], v[32:35]
	v_mfma_f32_16x16x32_bf16 v[28:31], v[140:143], v[208:211], v[28:31]
	v_mfma_f32_16x16x32_bf16 v[16:19], v[132:135], v[216:219], v[16:19]
	v_mfma_f32_16x16x32_bf16 v[12:15], v[140:143], v[216:219], v[12:15]
	v_mfma_f32_16x16x32_bf16 v[64:67], v[136:139], v[182:185], v[64:67]
	v_mfma_f32_16x16x32_bf16 v[60:63], v[144:147], v[182:185], v[60:63]
	v_mfma_f32_16x16x32_bf16 v[48:51], v[136:139], v[190:193], v[48:51]
	v_mfma_f32_16x16x32_bf16 v[44:47], v[144:147], v[190:193], v[44:47]
	v_mfma_f32_16x16x32_bf16 v[32:35], v[136:139], v[212:215], v[32:35]
	v_mfma_f32_16x16x32_bf16 v[28:31], v[144:147], v[212:215], v[28:31]
	v_mfma_f32_16x16x32_bf16 v[16:19], v[136:139], v[220:223], v[16:19]
	v_mfma_f32_16x16x32_bf16 v[12:15], v[144:147], v[220:223], v[12:15]
	s_setprio 0
	s_setprio 1
	v_mfma_f32_16x16x32_bf16 v[56:59], v[148:151], v[164:167], v[56:59]
	v_mfma_f32_16x16x32_bf16 v[52:55], v[156:159], v[164:167], v[52:55]
	v_mfma_f32_16x16x32_bf16 v[40:43], v[148:151], v[186:189], v[40:43]
	v_mfma_f32_16x16x32_bf16 v[36:39], v[156:159], v[186:189], v[36:39]
	v_mfma_f32_16x16x32_bf16 v[24:27], v[148:151], v[208:211], v[24:27]
	v_mfma_f32_16x16x32_bf16 v[20:23], v[156:159], v[208:211], v[20:23]
	v_mfma_f32_16x16x32_bf16 v[8:11], v[148:151], v[216:219], v[8:11]
	v_mfma_f32_16x16x32_bf16 v[4:7], v[156:159], v[216:219], v[4:7]
	v_mfma_f32_16x16x32_bf16 v[56:59], v[152:155], v[182:185], v[56:59]
	v_mfma_f32_16x16x32_bf16 v[52:55], v[160:163], v[182:185], v[52:55]
	v_mfma_f32_16x16x32_bf16 v[40:43], v[152:155], v[190:193], v[40:43]
	v_mfma_f32_16x16x32_bf16 v[36:39], v[160:163], v[190:193], v[36:39]
	v_mfma_f32_16x16x32_bf16 v[24:27], v[152:155], v[212:215], v[24:27]
	v_mfma_f32_16x16x32_bf16 v[20:23], v[160:163], v[212:215], v[20:23]
	v_mfma_f32_16x16x32_bf16 v[8:11], v[152:155], v[220:223], v[8:11]
	v_mfma_f32_16x16x32_bf16 v[4:7], v[160:163], v[220:223], v[4:7]
	s_setprio 0
	s_barrier
	s_add_i32 s45, s45, 2
	s_cmp_gt_u32 s45, 13
	s_cbranch_scc0 .LBB0_100
	s_and_b64 vcc, exec, s[14:15]
	s_cbranch_vccz .LBB0_103
	s_barrier

; #define PG8_STAGE(bufoff, gbase, voff) do { _Pragma("unroll") for (int _i = 0; _i < 2; ++_i) \
;         __builtin_amdgcn_global_load_lds((const unsigned*)((const char*)(gbase) + (voff)[_i]), (PG8_LAS unsigned*)(lds + (bufoff) + ldsw + _i * 8192), 16, 0, 0); } while (0)
; #define PG8_LDA(dst, b, h) do { _Pragma("unroll") for (int m = 0; m < 4; ++m) _Pragma("unroll") for (int k = 0; k < 2; ++k) dst[m][k] = *(const PG8_LAS bf16x8*)(lds + PG8_SA(b, h) + aoff + m * 2048 + k * 1024); } while (0)
; #define PG8_LDB(dst, b, h) do { _Pragma("unroll") for (int n = 0; n < 2; ++n) _Pragma("unroll") for (int k = 0; k < 2; ++k) dst[n][k] = *(const PG8_LAS bf16x8*)(lds + PG8_SB(b, h) + boff + n * 2048 + k * 1024); } while (0)
; #define PG8_MMA(ai, bj, At, Bt) do { __builtin_amdgcn_s_setprio(1); _Pragma("unroll") for (int m = 0; m < 4; ++m) _Pragma("unroll") for (int n = 0; n < 2; ++n) _Pragma("unroll") for (int k = 0; k < 2; ++k) \
;         acc[ai][bj][m][n] = __builtin_amdgcn_mfma_f32_16x16x32_bf16(Bt[n][k], At[m][k], acc[ai][bj][m][n], 0, 0, 0); __builtin_amdgcn_s_setprio(0); } while (0)
; #define PG8_WAIT_V(n) asm volatile("s_waitcnt vmcnt(" #n ")" ::: "memory")
; #define PG8_WAIT_L(n) asm volatile("s_waitcnt lgkmcnt(" #n ")" ::: "memory")
; #define PG8_BAR __builtin_amdgcn_s_barrier()
; #define PG8_SCHED __builtin_amdgcn_sched_barrier(0)
; template <class Epi, class Sched, bool ALIGN_EPI = false, bool SP2 = false>
; __device__ __forceinline__ void gemm_phase(PG8_LAS unsigned char* lds, const Gemm g, const Sched& S, const Epi& E) {
;     ...
;         for (int t = 0; t < nt; t += 2) {
;             const bool last = (t == nt - 2);
;             const char* a1 = cA + (size_t)(t + 1) * kstep;
;             const char* a2 = last ? nA : cA + (size_t)(t + 2) * kstep; const char* b2 = last ? nB : cB + (size_t)(t + 2) * kstep;
;             const char* a3 = a2 + kstep; const char* b3 = b2 + kstep;
;             if (last && has_next) S.a_ready(nxt);
;             if constexpr (SP2) {
;             PG8_LDB(B0, 0, 0); PG8_LDB(B1, 0, 1); PG8_SCHED; PG8_LDA(At, 0, 0); PG8_STAGE(PG8_SA(1, 1), a1 + hstep, voffA);
;             PG8_WAIT_V(8); PG8_WAIT_L(0); PG8_BAR; PG8_MMA(0, 0, At, B0); PG8_MMA(0, 1, At, B1); PG8_BAR; PG8_SCHED;
.LBB0_328:
	s_ashr_i32 s17, s16, 31
	s_lshl_b64 s[20:21], s[16:17], 19
	s_add_u32 s20, s37, s20
	s_addc_u32 s21, s38, s21
	s_and_b64 s[22:23], s[6:7], exec
	s_cselect_b32 s3, s21, s29
	s_cselect_b32 s17, s20, s28
	s_ashr_i32 s19, s18, 31
	s_lshl_b64 s[22:23], s[18:19], 19
	s_add_u32 s22, s39, s22
	s_addc_u32 s23, s40, s23
	s_and_b64 s[34:35], s[6:7], exec
	s_cselect_b32 s19, s23, s31
	s_cselect_b32 s25, s22, s30
	s_add_u32 s28, s28, 0x40080
	s_addc_u32 s29, s29, 0
	s_add_u32 s27, s30, 0x100
	s_addc_u32 s44, s31, 0
	s_mov_b32 s45, -2
	s_waitcnt vmcnt(0)
	s_add_u32 s30, s28, 0xfffc0080
	s_addc_u32 s31, s29, -1
	s_cmp_eq_u32 s45, 12
	s_cselect_b32 s35, s3, s31
	s_cselect_b32 s34, s17, s30
	s_cselect_b32 s31, s19, s44
	s_cselect_b32 s30, s25, s27
	ds_read_b128 v[108:111], v251
	ds_read_b128 v[112:115], v251 offset:1024
	ds_read_b128 v[124:127], v251 offset:2048
	ds_read_b128 v[128:131], v251 offset:3072
	ds_read_b128 v[132:135], v251 offset:16384
	ds_read_b128 v[140:143], v251 offset:17408
	ds_read_b128 v[148:151], v251 offset:18432
	ds_read_b128 v[156:159], v251 offset:19456
	v_lshl_add_u64 v[212:213], s[28:29], 0, v[208:209]
	s_add_i32 m0, s42, 0xc000
	ds_read_b128 v[164:167], v253
	ds_read_b128 v[168:171], v253 offset:1024
	ds_read_b128 v[172:175], v253 offset:2048
	ds_read_b128 v[176:179], v253 offset:3072
	ds_read_b128 v[180:183], v253 offset:4096
	ds_read_b128 v[184:187], v253 offset:5120
	ds_read_b128 v[188:191], v253 offset:6144
	ds_read_b128 v[192:195], v253 offset:7168
	global_load_lds_dwordx4 v[212:213], off
	s_add_i32 m0, s42, 0xe000
	v_lshl_add_u64 v[212:213], s[28:29], 0, v[210:211]
	global_load_lds_dwordx4 v[212:213], off
	s_waitcnt vmcnt(8) lgkmcnt(0)
	s_barrier
	s_setprio 1
	v_mfma_f32_16x16x32_bf16 v[160:163], v[108:111], v[164:167], 0
	v_mfma_f32_16x16x32_bf16 v[152:155], v[124:127], v[164:167], 0
	v_mfma_f32_16x16x32_bf16 v[120:123], v[108:111], v[172:175], 0
	v_mfma_f32_16x16x32_bf16 v[116:119], v[124:127], v[172:175], 0
	v_mfma_f32_16x16x32_bf16 v[96:99], v[108:111], v[180:183], 0
	v_mfma_f32_16x16x32_bf16 v[92:95], v[124:127], v[180:183], 0
	v_mfma_f32_16x16x32_bf16 v[80:83], v[108:111], v[188:191], 0
	v_mfma_f32_16x16x32_bf16 v[76:79], v[124:127], v[188:191], 0
	v_mfma_f32_16x16x32_bf16 v[160:163], v[112:115], v[168:171], v[160:163]
	v_mfma_f32_16x16x32_bf16 v[152:155], v[128:131], v[168:171], v[152:155]
	v_mfma_f32_16x16x32_bf16 v[120:123], v[112:115], v[176:179], v[120:123]
	v_mfma_f32_16x16x32_bf16 v[116:119], v[128:131], v[176:179], v[116:119]
	v_mfma_f32_16x16x32_bf16 v[96:99], v[112:115], v[184:187], v[96:99]
	v_mfma_f32_16x16x32_bf16 v[92:95], v[128:131], v[184:187], v[92:95]
	v_mfma_f32_16x16x32_bf16 v[80:83], v[112:115], v[192:195], v[80:83]
	v_mfma_f32_16x16x32_bf16 v[76:79], v[128:131], v[192:195], v[76:79]
	s_setprio 0
	s_setprio 1
	v_mfma_f32_16x16x32_bf16 v[144:147], v[132:135], v[164:167], 0
	v_mfma_f32_16x16x32_bf16 v[136:139], v[148:151], v[164:167], 0
	v_mfma_f32_16x16x32_bf16 v[104:107], v[132:135], v[172:175], 0
	v_mfma_f32_16x16x32_bf16 v[100:103], v[148:151], v[172:175], 0
	v_mfma_f32_16x16x32_bf16 v[88:91], v[132:135], v[180:183], 0
	v_mfma_f32_16x16x32_bf16 v[84:87], v[148:151], v[180:183], 0
	v_mfma_f32_16x16x32_bf16 v[72:75], v[132:135], v[188:191], 0
	v_mfma_f32_16x16x32_bf16 v[68:71], v[148:151], v[188:191], 0
	v_mfma_f32_16x16x32_bf16 v[144:147], v[140:143], v[168:171], v[144:147]
	v_mfma_f32_16x16x32_bf16 v[136:139], v[156:159], v[168:171], v[136:139]
	v_mfma_f32_16x16x32_bf16 v[104:107], v[140:143], v[176:179], v[104:107]
	v_mfma_f32_16x16x32_bf16 v[100:103], v[156:159], v[176:179], v[100:103]
	v_mfma_f32_16x16x32_bf16 v[88:91], v[140:143], v[184:187], v[88:91]
	v_mfma_f32_16x16x32_bf16 v[84:87], v[156:159], v[184:187], v[84:87]
	v_mfma_f32_16x16x32_bf16 v[72:75], v[140:143], v[192:195], v[72:75]
	v_mfma_f32_16x16x32_bf16 v[68:71], v[156:159], v[192:195], v[68:71]
	s_setprio 0
	s_barrier
; #define PG8_STAGE(bufoff, gbase, voff) do { _Pragma("unroll") for (int _i = 0; _i < 2; ++_i) \
;         __builtin_amdgcn_global_load_lds((const unsigned*)((const char*)(gbase) + (voff)[_i]), (PG8_LAS unsigned*)(lds + (bufoff) + ldsw + _i * 8192), 16, 0, 0); } while (0)
; #define PG8_LDA(dst, b, h) do { _Pragma("unroll") for (int m = 0; m < 4; ++m) _Pragma("unroll") for (int k = 0; k < 2; ++k) dst[m][k] = *(const PG8_LAS bf16x8*)(lds + PG8_SA(b, h) + aoff + m * 2048 + k * 1024); } while (0)
; #define PG8_MMA(ai, bj, At, Bt) do { __builtin_amdgcn_s_setprio(1); _Pragma("unroll") for (int m = 0; m < 4; ++m) _Pragma("unroll") for (int n = 0; n < 2; ++n) _Pragma("unroll") for (int k = 0; k < 2; ++k) \
;         acc[ai][bj][m][n] = __builtin_amdgcn_mfma_f32_16x16x32_bf16(Bt[n][k], At[m][k], acc[ai][bj][m][n], 0, 0, 0); __builtin_amdgcn_s_setprio(0); } while (0)
; #define PG8_WAIT_V(n) asm volatile("s_waitcnt vmcnt(" #n ")" ::: "memory")
; #define PG8_WAIT_L(n) asm volatile("s_waitcnt lgkmcnt(" #n ")" ::: "memory")
; #define PG8_BAR __builtin_amdgcn_s_barrier()
; #define PG8_SCHED __builtin_amdgcn_sched_barrier(0)
; template <class Epi, class Sched, bool ALIGN_EPI = false, bool SP2 = false>
; __device__ __forceinline__ void gemm_phase(PG8_LAS unsigned char* lds, const Gemm g, const Sched& S, const Epi& E) {
;     ...
;             PG8_LDA(At, 0, 1); PG8_STAGE(PG8_SB(0, 0), b2, voffB); PG8_STAGE(PG8_SB(0, 1), b2 + hstep, voffB); PG8_STAGE(PG8_SA(0, 0), a2, voffA);
;             PG8_WAIT_V(8); PG8_WAIT_L(0); PG8_BAR; PG8_MMA(1, 0, At, B0); PG8_MMA(1, 1, At, B1); PG8_BAR; PG8_SCHED;
	v_lshl_add_u64 v[212:213], s[30:31], 0, v[202:203]
	s_add_i32 m0, s41, 0x10000
	ds_read_b128 v[164:167], v253 offset:16384
	ds_read_b128 v[168:171], v253 offset:17408
	ds_read_b128 v[172:175], v253 offset:18432
	ds_read_b128 v[176:179], v253 offset:19456
	ds_read_b128 v[180:183], v253 offset:20480
	ds_read_b128 v[184:187], v253 offset:21504
	ds_read_b128 v[188:191], v253 offset:22528
	ds_read_b128 v[192:195], v253 offset:23552
	global_load_lds_dwordx4 v[212:213], off
	s_add_i32 m0, s41, 0x12000
	s_add_u32 s52, s30, 0x40000
	v_lshl_add_u64 v[214:215], s[30:31], 0, v[206:207]
	s_addc_u32 s53, s31, 0
	global_load_lds_dwordx4 v[214:215], off
	v_lshl_add_u64 v[216:217], s[52:53], 0, v[202:203]
	s_add_i32 m0, s41, 0x14000
	v_lshl_add_u64 v[218:219], s[34:35], 0, v[204:205]
	global_load_lds_dwordx4 v[216:217], off
	s_add_i32 m0, s41, 0x16000
	v_lshl_add_u64 v[216:217], s[52:53], 0, v[206:207]
	global_load_lds_dwordx4 v[216:217], off
	s_mov_b32 m0, s42
	v_lshl_add_u64 v[216:217], s[34:35], 0, v[0:1]
	global_load_lds_dwordx4 v[216:217], off
	s_mov_b32 m0, s43
	s_add_i32 s52, 0, 0x18000
	global_load_lds_dwordx4 v[218:219], off
	s_waitcnt vmcnt(8) lgkmcnt(0)
	s_barrier
	s_setprio 1
	v_mfma_f32_16x16x32_bf16 v[64:67], v[108:111], v[164:167], 0
	v_mfma_f32_16x16x32_bf16 v[60:63], v[124:127], v[164:167], 0
	v_mfma_f32_16x16x32_bf16 v[48:51], v[108:111], v[172:175], 0
	v_mfma_f32_16x16x32_bf16 v[44:47], v[124:127], v[172:175], 0
	v_mfma_f32_16x16x32_bf16 v[32:35], v[108:111], v[180:183], 0
	v_mfma_f32_16x16x32_bf16 v[28:31], v[124:127], v[180:183], 0
	v_mfma_f32_16x16x32_bf16 v[16:19], v[108:111], v[188:191], 0
	v_mfma_f32_16x16x32_bf16 v[12:15], v[124:127], v[188:191], 0
	v_mfma_f32_16x16x32_bf16 v[64:67], v[112:115], v[168:171], v[64:67]
	v_mfma_f32_16x16x32_bf16 v[60:63], v[128:131], v[168:171], v[60:63]
	v_mfma_f32_16x16x32_bf16 v[48:51], v[112:115], v[176:179], v[48:51]
	v_mfma_f32_16x16x32_bf16 v[44:47], v[128:131], v[176:179], v[44:47]
	v_mfma_f32_16x16x32_bf16 v[32:35], v[112:115], v[184:187], v[32:35]
	v_mfma_f32_16x16x32_bf16 v[28:31], v[128:131], v[184:187], v[28:31]
	v_mfma_f32_16x16x32_bf16 v[16:19], v[112:115], v[192:195], v[16:19]
	v_mfma_f32_16x16x32_bf16 v[12:15], v[128:131], v[192:195], v[12:15]
	s_setprio 0
	s_setprio 1
	v_mfma_f32_16x16x32_bf16 v[56:59], v[132:135], v[164:167], 0
	v_mfma_f32_16x16x32_bf16 v[52:55], v[148:151], v[164:167], 0
	v_mfma_f32_16x16x32_bf16 v[40:43], v[132:135], v[172:175], 0
	v_mfma_f32_16x16x32_bf16 v[36:39], v[148:151], v[172:175], 0
	v_mfma_f32_16x16x32_bf16 v[24:27], v[132:135], v[180:183], 0
	v_mfma_f32_16x16x32_bf16 v[20:23], v[148:151], v[180:183], 0
	v_mfma_f32_16x16x32_bf16 v[8:11], v[132:135], v[188:191], 0
	v_mfma_f32_16x16x32_bf16 v[4:7], v[148:151], v[188:191], 0
	v_mfma_f32_16x16x32_bf16 v[56:59], v[140:143], v[168:171], v[56:59]
	v_mfma_f32_16x16x32_bf16 v[52:55], v[156:159], v[168:171], v[52:55]
	v_mfma_f32_16x16x32_bf16 v[40:43], v[140:143], v[176:179], v[40:43]
	v_mfma_f32_16x16x32_bf16 v[36:39], v[156:159], v[176:179], v[36:39]
	v_mfma_f32_16x16x32_bf16 v[24:27], v[140:143], v[184:187], v[24:27]
	v_mfma_f32_16x16x32_bf16 v[20:23], v[156:159], v[184:187], v[20:23]
	v_mfma_f32_16x16x32_bf16 v[8:11], v[140:143], v[192:195], v[8:11]
	v_mfma_f32_16x16x32_bf16 v[4:7], v[156:159], v[192:195], v[4:7]
	s_setprio 0
	s_barrier
	s_branch .Lkmid_1

; #define PG8_STAGE(bufoff, gbase, voff) do { _Pragma("unroll") for (int _i = 0; _i < 2; ++_i) \
;         __builtin_amdgcn_global_load_lds((const unsigned*)((const char*)(gbase) + (voff)[_i]), (PG8_LAS unsigned*)(lds + (bufoff) + ldsw + _i * 8192), 16, 0, 0); } while (0)
; #define PG8_LDA(dst, b, h) do { _Pragma("unroll") for (int m = 0; m < 4; ++m) _Pragma("unroll") for (int k = 0; k < 2; ++k) dst[m][k] = *(const PG8_LAS bf16x8*)(lds + PG8_SA(b, h) + aoff + m * 2048 + k * 1024); } while (0)
; #define PG8_LDB(dst, b, h) do { _Pragma("unroll") for (int n = 0; n < 2; ++n) _Pragma("unroll") for (int k = 0; k < 2; ++k) dst[n][k] = *(const PG8_LAS bf16x8*)(lds + PG8_SB(b, h) + boff + n * 2048 + k * 1024); } while (0)
; #define PG8_MMA(ai, bj, At, Bt) do { __builtin_amdgcn_s_setprio(1); _Pragma("unroll") for (int m = 0; m < 4; ++m) _Pragma("unroll") for (int n = 0; n < 2; ++n) _Pragma("unroll") for (int k = 0; k < 2; ++k) \
;         acc[ai][bj][m][n] = __builtin_amdgcn_mfma_f32_16x16x32_bf16(Bt[n][k], At[m][k], acc[ai][bj][m][n], 0, 0, 0); __builtin_amdgcn_s_setprio(0); } while (0)
; #define PG8_WAIT_V(n) asm volatile("s_waitcnt vmcnt(" #n ")" ::: "memory")
; #define PG8_WAIT_L(n) asm volatile("s_waitcnt lgkmcnt(" #n ")" ::: "memory")
; #define PG8_BAR __builtin_amdgcn_s_barrier()
; #define PG8_SCHED __builtin_amdgcn_sched_barrier(0)
; template <class Epi, class Sched, bool ALIGN_EPI = false, bool SP2 = false>
; __device__ __forceinline__ void gemm_phase(PG8_LAS unsigned char* lds, const Gemm g, const Sched& S, const Epi& E) {
;     ...
;             PG8_LDB(B0, 1, 0); PG8_LDB(B1, 1, 1); PG8_SCHED; PG8_LDA(At, 1, 0); PG8_STAGE(PG8_SA(0, 1), a2 + hstep, voffA);
;             PG8_WAIT_V(8); PG8_WAIT_L(0); PG8_BAR; PG8_MMA(0, 0, At, B0); PG8_MMA(0, 1, At, B1); PG8_BAR; PG8_SCHED;
;             PG8_LDA(At, 1, 1); PG8_STAGE(PG8_SB(1, 0), b3, voffB); PG8_STAGE(PG8_SB(1, 1), b3 + hstep, voffB); PG8_STAGE(PG8_SA(1, 0), a3, voffA);
;             PG8_WAIT_V(8); PG8_WAIT_L(0); PG8_BAR; PG8_MMA(1, 0, At, B0); PG8_MMA(1, 1, At, B1); PG8_BAR; PG8_SCHED;
.Lkmid_1:
	ds_read_b128 v[108:111], v251 offset:32768
	ds_read_b128 v[112:115], v251 offset:33792
	ds_read_b128 v[124:127], v251 offset:34816
	ds_read_b128 v[128:131], v251 offset:35840
	ds_read_b128 v[132:135], v251 offset:49152
	ds_read_b128 v[140:143], v251 offset:50176
	ds_read_b128 v[148:151], v251 offset:51200
	ds_read_b128 v[156:159], v251 offset:52224
	s_add_u32 s34, s34, 0x40000
	s_addc_u32 s35, s35, 0
	s_mov_b32 m0, s46
	v_lshl_add_u64 v[220:221], s[34:35], 0, v[0:1]
	ds_read_b128 v[164:167], v253 offset:32768
	ds_read_b128 v[168:171], v253 offset:33792
	ds_read_b128 v[172:175], v253 offset:34816
	ds_read_b128 v[176:179], v253 offset:35840
	ds_read_b128 v[180:183], v253 offset:36864
	ds_read_b128 v[184:187], v253 offset:37888
	ds_read_b128 v[188:191], v253 offset:38912
	ds_read_b128 v[192:195], v253 offset:39936
	global_load_lds_dwordx4 v[220:221], off
	s_mov_b32 m0, s47
	v_lshl_add_u64 v[220:221], s[34:35], 0, v[204:205]
	global_load_lds_dwordx4 v[220:221], off
	s_waitcnt vmcnt(8) lgkmcnt(0)
	s_barrier
	s_setprio 1
	v_mfma_f32_16x16x32_bf16 v[160:163], v[108:111], v[164:167], v[160:163]
	v_mfma_f32_16x16x32_bf16 v[152:155], v[124:127], v[164:167], v[152:155]
	v_mfma_f32_16x16x32_bf16 v[120:123], v[108:111], v[172:175], v[120:123]
	v_mfma_f32_16x16x32_bf16 v[116:119], v[124:127], v[172:175], v[116:119]
	v_mfma_f32_16x16x32_bf16 v[96:99], v[108:111], v[180:183], v[96:99]
	v_mfma_f32_16x16x32_bf16 v[92:95], v[124:127], v[180:183], v[92:95]
	v_mfma_f32_16x16x32_bf16 v[80:83], v[108:111], v[188:191], v[80:83]
	v_mfma_f32_16x16x32_bf16 v[76:79], v[124:127], v[188:191], v[76:79]
	v_mfma_f32_16x16x32_bf16 v[160:163], v[112:115], v[168:171], v[160:163]
	v_mfma_f32_16x16x32_bf16 v[152:155], v[128:131], v[168:171], v[152:155]
	v_mfma_f32_16x16x32_bf16 v[120:123], v[112:115], v[176:179], v[120:123]
	v_mfma_f32_16x16x32_bf16 v[116:119], v[128:131], v[176:179], v[116:119]
	v_mfma_f32_16x16x32_bf16 v[96:99], v[112:115], v[184:187], v[96:99]
	v_mfma_f32_16x16x32_bf16 v[92:95], v[128:131], v[184:187], v[92:95]
	v_mfma_f32_16x16x32_bf16 v[80:83], v[112:115], v[192:195], v[80:83]
	v_mfma_f32_16x16x32_bf16 v[76:79], v[128:131], v[192:195], v[76:79]
	s_setprio 0
	s_setprio 1
	v_mfma_f32_16x16x32_bf16 v[144:147], v[132:135], v[164:167], v[144:147]
	v_mfma_f32_16x16x32_bf16 v[136:139], v[148:151], v[164:167], v[136:139]
	v_mfma_f32_16x16x32_bf16 v[104:107], v[132:135], v[172:175], v[104:107]
	v_mfma_f32_16x16x32_bf16 v[100:103], v[148:151], v[172:175], v[100:103]
	v_mfma_f32_16x16x32_bf16 v[88:91], v[132:135], v[180:183], v[88:91]
	v_mfma_f32_16x16x32_bf16 v[84:87], v[148:151], v[180:183], v[84:87]
	v_mfma_f32_16x16x32_bf16 v[72:75], v[132:135], v[188:191], v[72:75]
	v_mfma_f32_16x16x32_bf16 v[68:71], v[148:151], v[188:191], v[68:71]
	v_mfma_f32_16x16x32_bf16 v[144:147], v[140:143], v[168:171], v[144:147]
	v_mfma_f32_16x16x32_bf16 v[136:139], v[156:159], v[168:171], v[136:139]
	v_mfma_f32_16x16x32_bf16 v[104:107], v[140:143], v[176:179], v[104:107]
	v_mfma_f32_16x16x32_bf16 v[100:103], v[156:159], v[176:179], v[100:103]
	v_mfma_f32_16x16x32_bf16 v[88:91], v[140:143], v[184:187], v[88:91]
	v_mfma_f32_16x16x32_bf16 v[84:87], v[156:159], v[184:187], v[84:87]
	v_mfma_f32_16x16x32_bf16 v[72:75], v[140:143], v[192:195], v[72:75]
	v_mfma_f32_16x16x32_bf16 v[68:71], v[156:159], v[192:195], v[68:71]
	s_setprio 0
	s_barrier
	s_add_i32 m0, s41, 0x17f80
	ds_read_b128 v[164:167], v253 offset:49152
	ds_read_b128 v[168:171], v253 offset:50176
	ds_read_b128 v[172:175], v253 offset:51200
	ds_read_b128 v[176:179], v253 offset:52224
	ds_read_b128 v[180:183], v253 offset:53248
	ds_read_b128 v[184:187], v253 offset:54272
	ds_read_b128 v[188:191], v253 offset:55296
	ds_read_b128 v[192:195], v253 offset:56320
	global_load_lds_dwordx4 v[212:213], off offset:128
	s_add_i32 m0, s41, 0x19f80
	s_add_u32 s30, s30, 0x40080
	s_addc_u32 s31, s31, 0
	global_load_lds_dwordx4 v[214:215], off offset:128
	s_add_i32 m0, s41, 0x1c000
	v_lshl_add_u64 v[212:213], s[30:31], 0, v[202:203]
	global_load_lds_dwordx4 v[212:213], off
	s_add_i32 m0, s41, 0x1e000
	v_lshl_add_u64 v[212:213], s[30:31], 0, v[206:207]
	global_load_lds_dwordx4 v[212:213], off
	s_add_i32 m0, s49, 0xffffff80
	s_add_u32 s28, s28, 0x100
	s_addc_u32 s29, s29, 0
	global_load_lds_dwordx4 v[216:217], off offset:128
	s_add_i32 m0, s50, 0xffffff80
	s_add_u32 s27, s27, 0x100
	s_addc_u32 s44, s44, 0
	global_load_lds_dwordx4 v[218:219], off offset:128
	s_waitcnt vmcnt(8) lgkmcnt(0)
	s_barrier
	s_setprio 1
	v_mfma_f32_16x16x32_bf16 v[64:67], v[108:111], v[164:167], v[64:67]
	v_mfma_f32_16x16x32_bf16 v[60:63], v[124:127], v[164:167], v[60:63]
	v_mfma_f32_16x16x32_bf16 v[48:51], v[108:111], v[172:175], v[48:51]
	v_mfma_f32_16x16x32_bf16 v[44:47], v[124:127], v[172:175], v[44:47]
	v_mfma_f32_16x16x32_bf16 v[32:35], v[108:111], v[180:183], v[32:35]
	v_mfma_f32_16x16x32_bf16 v[28:31], v[124:127], v[180:183], v[28:31]
	v_mfma_f32_16x16x32_bf16 v[16:19], v[108:111], v[188:191], v[16:19]
	v_mfma_f32_16x16x32_bf16 v[12:15], v[124:127], v[188:191], v[12:15]
	v_mfma_f32_16x16x32_bf16 v[64:67], v[112:115], v[168:171], v[64:67]
	v_mfma_f32_16x16x32_bf16 v[60:63], v[128:131], v[168:171], v[60:63]
	v_mfma_f32_16x16x32_bf16 v[48:51], v[112:115], v[176:179], v[48:51]
	v_mfma_f32_16x16x32_bf16 v[44:47], v[128:131], v[176:179], v[44:47]
	v_mfma_f32_16x16x32_bf16 v[32:35], v[112:115], v[184:187], v[32:35]
	v_mfma_f32_16x16x32_bf16 v[28:31], v[128:131], v[184:187], v[28:31]
	v_mfma_f32_16x16x32_bf16 v[16:19], v[112:115], v[192:195], v[16:19]
	v_mfma_f32_16x16x32_bf16 v[12:15], v[128:131], v[192:195], v[12:15]
	s_setprio 0
	s_setprio 1
	v_mfma_f32_16x16x32_bf16 v[56:59], v[132:135], v[164:167], v[56:59]
	v_mfma_f32_16x16x32_bf16 v[52:55], v[148:151], v[164:167], v[52:55]
	v_mfma_f32_16x16x32_bf16 v[40:43], v[132:135], v[172:175], v[40:43]
	v_mfma_f32_16x16x32_bf16 v[36:39], v[148:151], v[172:175], v[36:39]
	v_mfma_f32_16x16x32_bf16 v[24:27], v[132:135], v[180:183], v[24:27]
	v_mfma_f32_16x16x32_bf16 v[20:23], v[148:151], v[180:183], v[20:23]
	v_mfma_f32_16x16x32_bf16 v[8:11], v[132:135], v[188:191], v[8:11]
	v_mfma_f32_16x16x32_bf16 v[4:7], v[148:151], v[188:191], v[4:7]
	v_mfma_f32_16x16x32_bf16 v[56:59], v[140:143], v[168:171], v[56:59]
	v_mfma_f32_16x16x32_bf16 v[52:55], v[156:159], v[168:171], v[52:55]
	v_mfma_f32_16x16x32_bf16 v[40:43], v[140:143], v[176:179], v[40:43]
	v_mfma_f32_16x16x32_bf16 v[36:39], v[156:159], v[176:179], v[36:39]
	v_mfma_f32_16x16x32_bf16 v[24:27], v[140:143], v[184:187], v[24:27]
	v_mfma_f32_16x16x32_bf16 v[20:23], v[156:159], v[184:187], v[20:23]
	v_mfma_f32_16x16x32_bf16 v[8:11], v[140:143], v[192:195], v[8:11]
	v_mfma_f32_16x16x32_bf16 v[4:7], v[156:159], v[192:195], v[4:7]
	s_setprio 0
	s_barrier
	s_add_i32 s45, s45, 2
	s_cmp_gt_u32 s45, 13
	s_cbranch_scc0 .LBB0_329
	s_and_b64 vcc, exec, s[14:15]
	s_cbranch_vccz .LBB0_332
	s_barrier

; #define PG8_STAGE(bufoff, gbase, voff) do { _Pragma("unroll") for (int _i = 0; _i < 2; ++_i) \
;         __builtin_amdgcn_global_load_lds((const unsigned*)((const char*)(gbase) + (voff)[_i]), (PG8_LAS unsigned*)(lds + (bufoff) + ldsw + _i * 8192), 16, 0, 0); } while (0)
; #define PG8_LDA(dst, b, h) do { _Pragma("unroll") for (int m = 0; m < 4; ++m) _Pragma("unroll") for (int k = 0; k < 2; ++k) dst[m][k] = *(const PG8_LAS bf16x8*)(lds + PG8_SA(b, h) + aoff + m * 2048 + k * 1024); } while (0)
; #define PG8_LDB(dst, b, h) do { _Pragma("unroll") for (int n = 0; n < 2; ++n) _Pragma("unroll") for (int k = 0; k < 2; ++k) dst[n][k] = *(const PG8_LAS bf16x8*)(lds + PG8_SB(b, h) + boff + n * 2048 + k * 1024); } while (0)
; #define PG8_MMA(ai, bj, At, Bt) do { __builtin_amdgcn_s_setprio(1); _Pragma("unroll") for (int m = 0; m < 4; ++m) _Pragma("unroll") for (int n = 0; n < 2; ++n) _Pragma("unroll") for (int k = 0; k < 2; ++k) \
;         acc[ai][bj][m][n] = __builtin_amdgcn_mfma_f32_16x16x32_bf16(Bt[n][k], At[m][k], acc[ai][bj][m][n], 0, 0, 0); __builtin_amdgcn_s_setprio(0); } while (0)
; #define PG8_WAIT_V(n) asm volatile("s_waitcnt vmcnt(" #n ")" ::: "memory")
; #define PG8_WAIT_L(n) asm volatile("s_waitcnt lgkmcnt(" #n ")" ::: "memory")
; #define PG8_BAR __builtin_amdgcn_s_barrier()
; #define PG8_SCHED __builtin_amdgcn_sched_barrier(0)
; template <class Epi, class Sched, bool ALIGN_EPI = false, bool SP2 = false>
; __device__ __forceinline__ void gemm_phase(PG8_LAS unsigned char* lds, const Gemm g, const Sched& S, const Epi& E) {
;     ...
;         for (int t = 0; t < nt; t += 2) {
;             const bool last = (t == nt - 2);
;             const char* a1 = cA + (size_t)(t + 1) * kstep;
;             const char* a2 = last ? nA : cA + (size_t)(t + 2) * kstep; const char* b2 = last ? nB : cB + (size_t)(t + 2) * kstep;
;             const char* a3 = a2 + kstep; const char* b3 = b2 + kstep;
;             if (last && has_next) S.a_ready(nxt);
;             if constexpr (SP2) {
;             PG8_LDB(B0, 0, 0); PG8_LDB(B1, 0, 1); PG8_SCHED; PG8_LDA(At, 0, 0); PG8_STAGE(PG8_SA(1, 1), a1 + hstep, voffA);
;             PG8_WAIT_V(8); PG8_WAIT_L(0); PG8_BAR; PG8_MMA(0, 0, At, B0); PG8_MMA(0, 1, At, B1); PG8_BAR; PG8_SCHED;
.LBB0_404:
	s_ashr_i32 s17, s16, 31
	s_lshl_b64 s[20:21], s[16:17], 19
	s_add_u32 s20, s29, s20
	s_addc_u32 s21, s30, s21
	s_and_b64 s[22:23], s[4:5], exec
	s_cselect_b32 s7, s21, s9
	s_cselect_b32 s17, s20, s8
	s_ashr_i32 s19, s18, 31
	s_lshl_b64 s[22:23], s[18:19], 19
	s_add_u32 s22, s31, s22
	s_addc_u32 s23, s34, s23
	s_and_b64 s[26:27], s[4:5], exec
	s_cselect_b32 s19, s23, s25
	s_cselect_b32 s43, s22, s24
	s_add_u32 s8, s8, 0x40080
	s_addc_u32 s9, s9, 0
	s_add_u32 s44, s24, 0x100
	s_addc_u32 s45, s25, 0
	s_mov_b32 s46, -2
	s_add_u32 s24, s8, 0xfffc0080
	s_addc_u32 s25, s9, -1
	s_cmp_eq_u32 s46, 12
	s_cselect_b32 s27, s7, s25
	s_cselect_b32 s26, s17, s24
	s_cselect_b32 s25, s19, s45
	s_cselect_b32 s24, s43, s44
	s_add_i32 s50, 0, 0x14000
	ds_read_b128 v[144:147], v164
	ds_read_b128 v[148:151], v164 offset:1024
	ds_read_b128 v[152:155], v164 offset:2048
	ds_read_b128 v[156:159], v164 offset:3072
	ds_read_b128 v[160:163], v164 offset:16384
	ds_read_b128 v[168:171], v164 offset:17408
	ds_read_b128 v[172:175], v164 offset:18432
	ds_read_b128 v[176:179], v164 offset:19456
	v_lshl_add_u64 v[198:199], s[8:9], 0, v[140:141]
	s_add_i32 m0, s37, 0xc000
	ds_read_b128 v[180:183], v166
	ds_read_b128 v[184:187], v166 offset:1024
	ds_read_b128 v[188:191], v166 offset:2048
	ds_read_b128 v[192:195], v166 offset:3072
	ds_read_b128 v[202:205], v166 offset:4096
	ds_read_b128 v[206:209], v166 offset:5120
	ds_read_b128 v[210:213], v166 offset:6144
	ds_read_b128 v[214:217], v166 offset:7168
	global_load_lds_dwordx4 v[198:199], off
	s_add_i32 m0, s37, 0xe000
	v_lshl_add_u64 v[198:199], s[8:9], 0, v[142:143]
	global_load_lds_dwordx4 v[198:199], off
	s_waitcnt vmcnt(8) lgkmcnt(0)
	s_barrier
	s_setprio 1
	v_mfma_f32_16x16x32_bf16 v[128:131], v[144:147], v[180:183], 0
	v_mfma_f32_16x16x32_bf16 v[120:123], v[152:155], v[180:183], 0
	v_mfma_f32_16x16x32_bf16 v[112:115], v[144:147], v[188:191], 0
	v_mfma_f32_16x16x32_bf16 v[104:107], v[152:155], v[188:191], 0
	v_mfma_f32_16x16x32_bf16 v[96:99], v[144:147], v[202:205], 0
	v_mfma_f32_16x16x32_bf16 v[88:91], v[152:155], v[202:205], 0
	v_mfma_f32_16x16x32_bf16 v[80:83], v[144:147], v[210:213], 0
	v_mfma_f32_16x16x32_bf16 v[72:75], v[152:155], v[210:213], 0
	v_mfma_f32_16x16x32_bf16 v[128:131], v[148:151], v[184:187], v[128:131]
	v_mfma_f32_16x16x32_bf16 v[120:123], v[156:159], v[184:187], v[120:123]
	v_mfma_f32_16x16x32_bf16 v[112:115], v[148:151], v[192:195], v[112:115]
	v_mfma_f32_16x16x32_bf16 v[104:107], v[156:159], v[192:195], v[104:107]
	v_mfma_f32_16x16x32_bf16 v[96:99], v[148:151], v[206:209], v[96:99]
	v_mfma_f32_16x16x32_bf16 v[88:91], v[156:159], v[206:209], v[88:91]
	v_mfma_f32_16x16x32_bf16 v[80:83], v[148:151], v[214:217], v[80:83]
	v_mfma_f32_16x16x32_bf16 v[72:75], v[156:159], v[214:217], v[72:75]
	s_setprio 0
	s_setprio 1
	v_mfma_f32_16x16x32_bf16 v[124:127], v[160:163], v[180:183], 0
	v_mfma_f32_16x16x32_bf16 v[116:119], v[172:175], v[180:183], 0
	v_mfma_f32_16x16x32_bf16 v[108:111], v[160:163], v[188:191], 0
	v_mfma_f32_16x16x32_bf16 v[100:103], v[172:175], v[188:191], 0
	v_mfma_f32_16x16x32_bf16 v[92:95], v[160:163], v[202:205], 0
	v_mfma_f32_16x16x32_bf16 v[84:87], v[172:175], v[202:205], 0
	v_mfma_f32_16x16x32_bf16 v[76:79], v[160:163], v[210:213], 0
	v_mfma_f32_16x16x32_bf16 v[68:71], v[172:175], v[210:213], 0
	v_mfma_f32_16x16x32_bf16 v[124:127], v[168:171], v[184:187], v[124:127]
	v_mfma_f32_16x16x32_bf16 v[116:119], v[176:179], v[184:187], v[116:119]
	v_mfma_f32_16x16x32_bf16 v[108:111], v[168:171], v[192:195], v[108:111]
	v_mfma_f32_16x16x32_bf16 v[100:103], v[176:179], v[192:195], v[100:103]
	v_mfma_f32_16x16x32_bf16 v[92:95], v[168:171], v[206:209], v[92:95]
	v_mfma_f32_16x16x32_bf16 v[84:87], v[176:179], v[206:209], v[84:87]
	v_mfma_f32_16x16x32_bf16 v[76:79], v[168:171], v[214:217], v[76:79]
	v_mfma_f32_16x16x32_bf16 v[68:71], v[176:179], v[214:217], v[68:71]
	s_setprio 0
	s_barrier
; #define PG8_STAGE(bufoff, gbase, voff) do { _Pragma("unroll") for (int _i = 0; _i < 2; ++_i) \
;         __builtin_amdgcn_global_load_lds((const unsigned*)((const char*)(gbase) + (voff)[_i]), (PG8_LAS unsigned*)(lds + (bufoff) + ldsw + _i * 8192), 16, 0, 0); } while (0)
; #define PG8_LDA(dst, b, h) do { _Pragma("unroll") for (int m = 0; m < 4; ++m) _Pragma("unroll") for (int k = 0; k < 2; ++k) dst[m][k] = *(const PG8_LAS bf16x8*)(lds + PG8_SA(b, h) + aoff + m * 2048 + k * 1024); } while (0)
; #define PG8_MMA(ai, bj, At, Bt) do { __builtin_amdgcn_s_setprio(1); _Pragma("unroll") for (int m = 0; m < 4; ++m) _Pragma("unroll") for (int n = 0; n < 2; ++n) _Pragma("unroll") for (int k = 0; k < 2; ++k) \
;         acc[ai][bj][m][n] = __builtin_amdgcn_mfma_f32_16x16x32_bf16(Bt[n][k], At[m][k], acc[ai][bj][m][n], 0, 0, 0); __builtin_amdgcn_s_setprio(0); } while (0)
; #define PG8_WAIT_V(n) asm volatile("s_waitcnt vmcnt(" #n ")" ::: "memory")
; #define PG8_WAIT_L(n) asm volatile("s_waitcnt lgkmcnt(" #n ")" ::: "memory")
; #define PG8_BAR __builtin_amdgcn_s_barrier()
; #define PG8_SCHED __builtin_amdgcn_sched_barrier(0)
; template <class Epi, class Sched, bool ALIGN_EPI = false, bool SP2 = false>
; __device__ __forceinline__ void gemm_phase(PG8_LAS unsigned char* lds, const Gemm g, const Sched& S, const Epi& E) {
;     ...
;             PG8_LDA(At, 0, 1); PG8_STAGE(PG8_SB(0, 0), b2, voffB); PG8_STAGE(PG8_SB(0, 1), b2 + hstep, voffB); PG8_STAGE(PG8_SA(0, 0), a2, voffA);
;             PG8_WAIT_V(8); PG8_WAIT_L(0); PG8_BAR; PG8_MMA(1, 0, At, B0); PG8_MMA(1, 1, At, B1); PG8_BAR; PG8_SCHED;
	v_lshl_add_u64 v[198:199], s[24:25], 0, v[134:135]
	s_add_i32 m0, s35, 0x10000
	ds_read_b128 v[180:183], v166 offset:16384
	ds_read_b128 v[184:187], v166 offset:17408
	ds_read_b128 v[188:191], v166 offset:18432
	ds_read_b128 v[192:195], v166 offset:19456
	ds_read_b128 v[202:205], v166 offset:20480
	ds_read_b128 v[206:209], v166 offset:21504
	ds_read_b128 v[210:213], v166 offset:22528
	ds_read_b128 v[214:217], v166 offset:23552
	global_load_lds_dwordx4 v[198:199], off
	s_add_i32 m0, s35, 0x12000
	s_add_u32 s48, s24, 0x40000
	v_lshl_add_u64 v[218:219], s[24:25], 0, v[0:1]
	s_addc_u32 s49, s25, 0
	global_load_lds_dwordx4 v[218:219], off
	v_lshl_add_u64 v[220:221], s[48:49], 0, v[134:135]
	s_add_i32 m0, s35, 0x14000
	v_lshl_add_u64 v[222:223], s[26:27], 0, v[132:133]
	global_load_lds_dwordx4 v[220:221], off
	s_add_i32 m0, s35, 0x16000
	v_lshl_add_u64 v[220:221], s[48:49], 0, v[0:1]
	global_load_lds_dwordx4 v[220:221], off
	s_mov_b32 m0, s37
	v_lshl_add_u64 v[220:221], s[26:27], 0, v[136:137]
	global_load_lds_dwordx4 v[220:221], off
	s_mov_b32 m0, s38
	s_add_i32 s47, 0, 0x18000
	global_load_lds_dwordx4 v[222:223], off
	s_waitcnt vmcnt(8) lgkmcnt(0)
	s_barrier
	s_setprio 1
	v_mfma_f32_16x16x32_bf16 v[64:67], v[144:147], v[180:183], 0
	v_mfma_f32_16x16x32_bf16 v[56:59], v[152:155], v[180:183], 0
	v_mfma_f32_16x16x32_bf16 v[48:51], v[144:147], v[188:191], 0
	v_mfma_f32_16x16x32_bf16 v[40:43], v[152:155], v[188:191], 0
	v_mfma_f32_16x16x32_bf16 v[32:35], v[144:147], v[202:205], 0
	v_mfma_f32_16x16x32_bf16 v[24:27], v[152:155], v[202:205], 0
	v_mfma_f32_16x16x32_bf16 v[16:19], v[144:147], v[210:213], 0
	v_mfma_f32_16x16x32_bf16 v[8:11], v[152:155], v[210:213], 0
	v_mfma_f32_16x16x32_bf16 v[64:67], v[148:151], v[184:187], v[64:67]
	v_mfma_f32_16x16x32_bf16 v[56:59], v[156:159], v[184:187], v[56:59]
	v_mfma_f32_16x16x32_bf16 v[48:51], v[148:151], v[192:195], v[48:51]
	v_mfma_f32_16x16x32_bf16 v[40:43], v[156:159], v[192:195], v[40:43]
	v_mfma_f32_16x16x32_bf16 v[32:35], v[148:151], v[206:209], v[32:35]
	v_mfma_f32_16x16x32_bf16 v[24:27], v[156:159], v[206:209], v[24:27]
	v_mfma_f32_16x16x32_bf16 v[16:19], v[148:151], v[214:217], v[16:19]
	v_mfma_f32_16x16x32_bf16 v[8:11], v[156:159], v[214:217], v[8:11]
	s_setprio 0
	s_setprio 1
	v_mfma_f32_16x16x32_bf16 v[60:63], v[160:163], v[180:183], 0
	v_mfma_f32_16x16x32_bf16 v[52:55], v[172:175], v[180:183], 0
	v_mfma_f32_16x16x32_bf16 v[44:47], v[160:163], v[188:191], 0
	v_mfma_f32_16x16x32_bf16 v[36:39], v[172:175], v[188:191], 0
	v_mfma_f32_16x16x32_bf16 v[28:31], v[160:163], v[202:205], 0
	v_mfma_f32_16x16x32_bf16 v[20:23], v[172:175], v[202:205], 0
	v_mfma_f32_16x16x32_bf16 v[12:15], v[160:163], v[210:213], 0
	v_mfma_f32_16x16x32_bf16 v[4:7], v[172:175], v[210:213], 0
	v_mfma_f32_16x16x32_bf16 v[60:63], v[168:171], v[184:187], v[60:63]
	v_mfma_f32_16x16x32_bf16 v[52:55], v[176:179], v[184:187], v[52:55]
	v_mfma_f32_16x16x32_bf16 v[44:47], v[168:171], v[192:195], v[44:47]
	v_mfma_f32_16x16x32_bf16 v[36:39], v[176:179], v[192:195], v[36:39]
	v_mfma_f32_16x16x32_bf16 v[28:31], v[168:171], v[206:209], v[28:31]
	v_mfma_f32_16x16x32_bf16 v[20:23], v[176:179], v[206:209], v[20:23]
	v_mfma_f32_16x16x32_bf16 v[12:15], v[168:171], v[214:217], v[12:15]
	v_mfma_f32_16x16x32_bf16 v[4:7], v[176:179], v[214:217], v[4:7]
	s_setprio 0
	s_barrier
	s_branch .Lkmid_2

; #define PG8_STAGE(bufoff, gbase, voff) do { _Pragma("unroll") for (int _i = 0; _i < 2; ++_i) \
;         __builtin_amdgcn_global_load_lds((const unsigned*)((const char*)(gbase) + (voff)[_i]), (PG8_LAS unsigned*)(lds + (bufoff) + ldsw + _i * 8192), 16, 0, 0); } while (0)
; #define PG8_LDA(dst, b, h) do { _Pragma("unroll") for (int m = 0; m < 4; ++m) _Pragma("unroll") for (int k = 0; k < 2; ++k) dst[m][k] = *(const PG8_LAS bf16x8*)(lds + PG8_SA(b, h) + aoff + m * 2048 + k * 1024); } while (0)
; #define PG8_LDB(dst, b, h) do { _Pragma("unroll") for (int n = 0; n < 2; ++n) _Pragma("unroll") for (int k = 0; k < 2; ++k) dst[n][k] = *(const PG8_LAS bf16x8*)(lds + PG8_SB(b, h) + boff + n * 2048 + k * 1024); } while (0)
; #define PG8_MMA(ai, bj, At, Bt) do { __builtin_amdgcn_s_setprio(1); _Pragma("unroll") for (int m = 0; m < 4; ++m) _Pragma("unroll") for (int n = 0; n < 2; ++n) _Pragma("unroll") for (int k = 0; k < 2; ++k) \
;         acc[ai][bj][m][n] = __builtin_amdgcn_mfma_f32_16x16x32_bf16(Bt[n][k], At[m][k], acc[ai][bj][m][n], 0, 0, 0); __builtin_amdgcn_s_setprio(0); } while (0)
; #define PG8_WAIT_V(n) asm volatile("s_waitcnt vmcnt(" #n ")" ::: "memory")
; #define PG8_WAIT_L(n) asm volatile("s_waitcnt lgkmcnt(" #n ")" ::: "memory")
; #define PG8_BAR __builtin_amdgcn_s_barrier()
; #define PG8_SCHED __builtin_amdgcn_sched_barrier(0)
; template <class Epi, class Sched, bool ALIGN_EPI = false, bool SP2 = false>
; __device__ __forceinline__ void gemm_phase(PG8_LAS unsigned char* lds, const Gemm g, const Sched& S, const Epi& E) {
;     ...
;             PG8_LDB(B0, 1, 0); PG8_LDB(B1, 1, 1); PG8_SCHED; PG8_LDA(At, 1, 0); PG8_STAGE(PG8_SA(0, 1), a2 + hstep, voffA);
;             PG8_WAIT_V(8); PG8_WAIT_L(0); PG8_BAR; PG8_MMA(0, 0, At, B0); PG8_MMA(0, 1, At, B1); PG8_BAR; PG8_SCHED;
;             PG8_LDA(At, 1, 1); PG8_STAGE(PG8_SB(1, 0), b3, voffB); PG8_STAGE(PG8_SB(1, 1), b3 + hstep, voffB); PG8_STAGE(PG8_SA(1, 0), a3, voffA);
;             PG8_WAIT_V(8); PG8_WAIT_L(0); PG8_BAR; PG8_MMA(1, 0, At, B0); PG8_MMA(1, 1, At, B1); PG8_BAR; PG8_SCHED;
.Lkmid_2:
	ds_read_b128 v[144:147], v164 offset:32768
	ds_read_b128 v[148:151], v164 offset:33792
	ds_read_b128 v[152:155], v164 offset:34816
	ds_read_b128 v[156:159], v164 offset:35840
	ds_read_b128 v[160:163], v164 offset:49152
	ds_read_b128 v[168:171], v164 offset:50176
	ds_read_b128 v[172:175], v164 offset:51200
	ds_read_b128 v[176:179], v164 offset:52224
	s_add_u32 s26, s26, 0x40000
	s_addc_u32 s27, s27, 0
	s_mov_b32 m0, s39
	v_lshl_add_u64 v[224:225], s[26:27], 0, v[136:137]
	ds_read_b128 v[180:183], v166 offset:32768
	ds_read_b128 v[184:187], v166 offset:33792
	ds_read_b128 v[188:191], v166 offset:34816
	ds_read_b128 v[192:195], v166 offset:35840
	ds_read_b128 v[202:205], v166 offset:36864
	ds_read_b128 v[206:209], v166 offset:37888
	ds_read_b128 v[210:213], v166 offset:38912
	ds_read_b128 v[214:217], v166 offset:39936
	global_load_lds_dwordx4 v[224:225], off
	s_mov_b32 m0, s40
	v_lshl_add_u64 v[224:225], s[26:27], 0, v[132:133]
	global_load_lds_dwordx4 v[224:225], off
	s_waitcnt vmcnt(8) lgkmcnt(0)
	s_barrier
	s_setprio 1
	v_mfma_f32_16x16x32_bf16 v[128:131], v[144:147], v[180:183], v[128:131]
	v_mfma_f32_16x16x32_bf16 v[120:123], v[152:155], v[180:183], v[120:123]
	v_mfma_f32_16x16x32_bf16 v[112:115], v[144:147], v[188:191], v[112:115]
	v_mfma_f32_16x16x32_bf16 v[104:107], v[152:155], v[188:191], v[104:107]
	v_mfma_f32_16x16x32_bf16 v[96:99], v[144:147], v[202:205], v[96:99]
	v_mfma_f32_16x16x32_bf16 v[88:91], v[152:155], v[202:205], v[88:91]
	v_mfma_f32_16x16x32_bf16 v[80:83], v[144:147], v[210:213], v[80:83]
	v_mfma_f32_16x16x32_bf16 v[72:75], v[152:155], v[210:213], v[72:75]
	v_mfma_f32_16x16x32_bf16 v[128:131], v[148:151], v[184:187], v[128:131]
	v_mfma_f32_16x16x32_bf16 v[120:123], v[156:159], v[184:187], v[120:123]
	v_mfma_f32_16x16x32_bf16 v[112:115], v[148:151], v[192:195], v[112:115]
	v_mfma_f32_16x16x32_bf16 v[104:107], v[156:159], v[192:195], v[104:107]
	v_mfma_f32_16x16x32_bf16 v[96:99], v[148:151], v[206:209], v[96:99]
	v_mfma_f32_16x16x32_bf16 v[88:91], v[156:159], v[206:209], v[88:91]
	v_mfma_f32_16x16x32_bf16 v[80:83], v[148:151], v[214:217], v[80:83]
	v_mfma_f32_16x16x32_bf16 v[72:75], v[156:159], v[214:217], v[72:75]
	s_setprio 0
	s_setprio 1
	v_mfma_f32_16x16x32_bf16 v[124:127], v[160:163], v[180:183], v[124:127]
	v_mfma_f32_16x16x32_bf16 v[116:119], v[172:175], v[180:183], v[116:119]
	v_mfma_f32_16x16x32_bf16 v[108:111], v[160:163], v[188:191], v[108:111]
	v_mfma_f32_16x16x32_bf16 v[100:103], v[172:175], v[188:191], v[100:103]
	v_mfma_f32_16x16x32_bf16 v[92:95], v[160:163], v[202:205], v[92:95]
	v_mfma_f32_16x16x32_bf16 v[84:87], v[172:175], v[202:205], v[84:87]
	v_mfma_f32_16x16x32_bf16 v[76:79], v[160:163], v[210:213], v[76:79]
	v_mfma_f32_16x16x32_bf16 v[68:71], v[172:175], v[210:213], v[68:71]
	v_mfma_f32_16x16x32_bf16 v[124:127], v[168:171], v[184:187], v[124:127]
	v_mfma_f32_16x16x32_bf16 v[116:119], v[176:179], v[184:187], v[116:119]
	v_mfma_f32_16x16x32_bf16 v[108:111], v[168:171], v[192:195], v[108:111]
	v_mfma_f32_16x16x32_bf16 v[100:103], v[176:179], v[192:195], v[100:103]
	v_mfma_f32_16x16x32_bf16 v[92:95], v[168:171], v[206:209], v[92:95]
	v_mfma_f32_16x16x32_bf16 v[84:87], v[176:179], v[206:209], v[84:87]
	v_mfma_f32_16x16x32_bf16 v[76:79], v[168:171], v[214:217], v[76:79]
	v_mfma_f32_16x16x32_bf16 v[68:71], v[176:179], v[214:217], v[68:71]
	s_setprio 0
	s_barrier
	s_add_i32 m0, s35, 0x17f80
	ds_read_b128 v[180:183], v166 offset:49152
	ds_read_b128 v[184:187], v166 offset:50176
	ds_read_b128 v[188:191], v166 offset:51200
	ds_read_b128 v[192:195], v166 offset:52224
	ds_read_b128 v[202:205], v166 offset:53248
	ds_read_b128 v[206:209], v166 offset:54272
	ds_read_b128 v[210:213], v166 offset:55296
	ds_read_b128 v[214:217], v166 offset:56320
	global_load_lds_dwordx4 v[198:199], off offset:128
	s_add_i32 m0, s35, 0x19f80
	s_add_u32 s24, s24, 0x40080
	s_addc_u32 s25, s25, 0
	global_load_lds_dwordx4 v[218:219], off offset:128
	s_add_i32 m0, s35, 0x1c000
	v_lshl_add_u64 v[198:199], s[24:25], 0, v[134:135]
	global_load_lds_dwordx4 v[198:199], off
	s_add_i32 m0, s35, 0x1e000
	v_lshl_add_u64 v[198:199], s[24:25], 0, v[0:1]
	global_load_lds_dwordx4 v[198:199], off
	s_add_i32 m0, s41, 0xffffff80
	s_add_u32 s8, s8, 0x100
	s_addc_u32 s9, s9, 0
	global_load_lds_dwordx4 v[220:221], off offset:128
	s_add_i32 m0, s42, 0xffffff80
	s_add_u32 s44, s44, 0x100
	s_addc_u32 s45, s45, 0
	global_load_lds_dwordx4 v[222:223], off offset:128
	s_waitcnt vmcnt(8) lgkmcnt(0)
	s_barrier
	s_setprio 1
	v_mfma_f32_16x16x32_bf16 v[64:67], v[144:147], v[180:183], v[64:67]
	v_mfma_f32_16x16x32_bf16 v[56:59], v[152:155], v[180:183], v[56:59]
	v_mfma_f32_16x16x32_bf16 v[48:51], v[144:147], v[188:191], v[48:51]
	v_mfma_f32_16x16x32_bf16 v[40:43], v[152:155], v[188:191], v[40:43]
	v_mfma_f32_16x16x32_bf16 v[32:35], v[144:147], v[202:205], v[32:35]
	v_mfma_f32_16x16x32_bf16 v[24:27], v[152:155], v[202:205], v[24:27]
	v_mfma_f32_16x16x32_bf16 v[16:19], v[144:147], v[210:213], v[16:19]
	v_mfma_f32_16x16x32_bf16 v[8:11], v[152:155], v[210:213], v[8:11]
	v_mfma_f32_16x16x32_bf16 v[64:67], v[148:151], v[184:187], v[64:67]
	v_mfma_f32_16x16x32_bf16 v[56:59], v[156:159], v[184:187], v[56:59]
	v_mfma_f32_16x16x32_bf16 v[48:51], v[148:151], v[192:195], v[48:51]
	v_mfma_f32_16x16x32_bf16 v[40:43], v[156:159], v[192:195], v[40:43]
	v_mfma_f32_16x16x32_bf16 v[32:35], v[148:151], v[206:209], v[32:35]
	v_mfma_f32_16x16x32_bf16 v[24:27], v[156:159], v[206:209], v[24:27]
	v_mfma_f32_16x16x32_bf16 v[16:19], v[148:151], v[214:217], v[16:19]
	v_mfma_f32_16x16x32_bf16 v[8:11], v[156:159], v[214:217], v[8:11]
	s_setprio 0
	s_setprio 1
	v_mfma_f32_16x16x32_bf16 v[60:63], v[160:163], v[180:183], v[60:63]
	v_mfma_f32_16x16x32_bf16 v[52:55], v[172:175], v[180:183], v[52:55]
	v_mfma_f32_16x16x32_bf16 v[44:47], v[160:163], v[188:191], v[44:47]
	v_mfma_f32_16x16x32_bf16 v[36:39], v[172:175], v[188:191], v[36:39]
	v_mfma_f32_16x16x32_bf16 v[28:31], v[160:163], v[202:205], v[28:31]
	v_mfma_f32_16x16x32_bf16 v[20:23], v[172:175], v[202:205], v[20:23]
	v_mfma_f32_16x16x32_bf16 v[12:15], v[160:163], v[210:213], v[12:15]
	v_mfma_f32_16x16x32_bf16 v[4:7], v[172:175], v[210:213], v[4:7]
	v_mfma_f32_16x16x32_bf16 v[60:63], v[168:171], v[184:187], v[60:63]
	v_mfma_f32_16x16x32_bf16 v[52:55], v[176:179], v[184:187], v[52:55]
	v_mfma_f32_16x16x32_bf16 v[44:47], v[168:171], v[192:195], v[44:47]
	v_mfma_f32_16x16x32_bf16 v[36:39], v[176:179], v[192:195], v[36:39]
	v_mfma_f32_16x16x32_bf16 v[28:31], v[168:171], v[206:209], v[28:31]
	v_mfma_f32_16x16x32_bf16 v[20:23], v[176:179], v[206:209], v[20:23]
	v_mfma_f32_16x16x32_bf16 v[12:15], v[168:171], v[214:217], v[12:15]
	v_mfma_f32_16x16x32_bf16 v[4:7], v[176:179], v[214:217], v[4:7]
	s_setprio 0
	s_barrier
	s_add_i32 s46, s46, 2
	s_cmp_gt_u32 s46, 13
	s_cbranch_scc0 .LBB0_405
	s_and_b64 vcc, exec, s[14:15]
	s_cbranch_vccz .LBB0_408
	s_barrier

; #define PG8_STAGE(bufoff, gbase, voff) do { _Pragma("unroll") for (int _i = 0; _i < 2; ++_i) \
;         __builtin_amdgcn_global_load_lds((const unsigned*)((const char*)(gbase) + (voff)[_i]), (PG8_LAS unsigned*)(lds + (bufoff) + ldsw + _i * 8192), 16, 0, 0); } while (0)
; #define PG8_LDA(dst, b, h) do { _Pragma("unroll") for (int m = 0; m < 4; ++m) _Pragma("unroll") for (int k = 0; k < 2; ++k) dst[m][k] = *(const PG8_LAS bf16x8*)(lds + PG8_SA(b, h) + aoff + m * 2048 + k * 1024); } while (0)
; #define PG8_LDB(dst, b, h) do { _Pragma("unroll") for (int n = 0; n < 2; ++n) _Pragma("unroll") for (int k = 0; k < 2; ++k) dst[n][k] = *(const PG8_LAS bf16x8*)(lds + PG8_SB(b, h) + boff + n * 2048 + k * 1024); } while (0)
; #define PG8_MMA(ai, bj, At, Bt) do { __builtin_amdgcn_s_setprio(1); _Pragma("unroll") for (int m = 0; m < 4; ++m) _Pragma("unroll") for (int n = 0; n < 2; ++n) _Pragma("unroll") for (int k = 0; k < 2; ++k) \
;         acc[ai][bj][m][n] = __builtin_amdgcn_mfma_f32_16x16x32_bf16(Bt[n][k], At[m][k], acc[ai][bj][m][n], 0, 0, 0); __builtin_amdgcn_s_setprio(0); } while (0)
; #define PG8_WAIT_V(n) asm volatile("s_waitcnt vmcnt(" #n ")" ::: "memory")
; #define PG8_BAR __builtin_amdgcn_s_barrier()
; template <class Epi, class Sched, bool ALIGN_EPI = false, bool SP2 = false>
; __device__ __forceinline__ void gemm_phase(PG8_LAS unsigned char* lds, const Gemm g, const Sched& S, const Epi& E) {
;     ...
;         for (int t = 0; t < nt; t += 2) {
;             const bool last = (t == nt - 2);
;             const char* a1 = cA + (size_t)(t + 1) * kstep;
;             const char* a2 = last ? nA : cA + (size_t)(t + 2) * kstep; const char* b2 = last ? nB : cB + (size_t)(t + 2) * kstep;
;             const char* a3 = a2 + kstep; const char* b3 = b2 + kstep;
;             if (last && has_next) S.a_ready(nxt);
;             if constexpr (SP2) {
;             PG8_LDB(B0, 0, 0); PG8_LDB(B1, 0, 1); PG8_SCHED; PG8_LDA(At, 0, 0); PG8_STAGE(PG8_SA(1, 1), a1 + hstep, voffA);
;             PG8_WAIT_V(8); PG8_WAIT_L(0); PG8_BAR; PG8_MMA(0, 0, At, B0); PG8_MMA(0, 1, At, B1); PG8_BAR; PG8_SCHED;
;             PG8_LDA(At, 0, 1); PG8_STAGE(PG8_SB(0, 0), b2, voffB); PG8_STAGE(PG8_SB(0, 1), b2 + hstep, voffB); PG8_STAGE(PG8_SA(0, 0), a2, voffA);
;             PG8_WAIT_V(8); PG8_WAIT_L(0); PG8_BAR; PG8_MMA(1, 0, At, B0); PG8_MMA(1, 1, At, B1); PG8_BAR; PG8_SCHED;
.LBB0_479:
	s_add_u32 s44, s28, 0x100
	s_addc_u32 s45, s29, 0
	s_mov_b32 s53, -2
	s_waitcnt vmcnt(0)
	s_add_u32 s8, s26, 0x100
	s_addc_u32 s9, s27, 0
	s_cmp_eq_u32 s53, 40
	s_cselect_b32 s31, s23, s9
	s_cselect_b32 s30, s22, s8
	s_cselect_b32 s29, s25, s45
	s_cselect_b32 s28, s24, s44
	ds_read_b128 v[68:71], v234
	ds_read_b128 v[80:83], v234 offset:1024
	ds_read_b128 v[92:95], v234 offset:2048
	ds_read_b128 v[100:103], v234 offset:3072
	ds_read_b128 v[112:115], v234 offset:16384
	ds_read_b128 v[120:123], v234 offset:17408
	ds_read_b128 v[132:135], v234 offset:18432
	ds_read_b128 v[144:147], v234 offset:19456
	v_lshl_add_u64 v[198:199], s[26:27], 0, v[204:205]
	s_add_i32 m0, s40, 0xc000
	ds_read_b128 v[156:159], v236
	ds_read_b128 v[168:171], v236 offset:1024
	ds_read_b128 v[172:175], v236 offset:2048
	ds_read_b128 v[176:179], v236 offset:3072
	ds_read_b128 v[180:183], v236 offset:4096
	ds_read_b128 v[184:187], v236 offset:5120
	ds_read_b128 v[188:191], v236 offset:6144
	ds_read_b128 v[208:211], v236 offset:7168
	global_load_lds_dwordx4 v[198:199], off
	s_add_i32 m0, s40, 0xe000
	v_lshl_add_u64 v[198:199], s[26:27], 0, v[206:207]
	global_load_lds_dwordx4 v[198:199], off
	s_waitcnt vmcnt(8) lgkmcnt(0)
	s_barrier
	s_setprio 1
	v_mfma_f32_16x16x32_bf16 v[164:167], v[68:71], v[156:159], 0
	v_mfma_f32_16x16x32_bf16 v[160:163], v[92:95], v[156:159], 0
	v_mfma_f32_16x16x32_bf16 v[140:143], v[68:71], v[172:175], 0
	v_mfma_f32_16x16x32_bf16 v[136:139], v[92:95], v[172:175], 0
	v_mfma_f32_16x16x32_bf16 v[116:119], v[68:71], v[180:183], 0
	v_mfma_f32_16x16x32_bf16 v[108:111], v[92:95], v[180:183], 0
	v_mfma_f32_16x16x32_bf16 v[88:91], v[68:71], v[188:191], 0
	v_mfma_f32_16x16x32_bf16 v[84:87], v[92:95], v[188:191], 0
	v_mfma_f32_16x16x32_bf16 v[164:167], v[80:83], v[168:171], v[164:167]
	v_mfma_f32_16x16x32_bf16 v[160:163], v[100:103], v[168:171], v[160:163]
	v_mfma_f32_16x16x32_bf16 v[140:143], v[80:83], v[176:179], v[140:143]
	v_mfma_f32_16x16x32_bf16 v[136:139], v[100:103], v[176:179], v[136:139]
	v_mfma_f32_16x16x32_bf16 v[116:119], v[80:83], v[184:187], v[116:119]
	v_mfma_f32_16x16x32_bf16 v[108:111], v[100:103], v[184:187], v[108:111]
	v_mfma_f32_16x16x32_bf16 v[88:91], v[80:83], v[208:211], v[88:91]
	v_mfma_f32_16x16x32_bf16 v[84:87], v[100:103], v[208:211], v[84:87]
	s_setprio 0
	s_setprio 1
	v_mfma_f32_16x16x32_bf16 v[152:155], v[112:115], v[156:159], 0
	v_mfma_f32_16x16x32_bf16 v[148:151], v[132:135], v[156:159], 0
	v_mfma_f32_16x16x32_bf16 v[128:131], v[112:115], v[172:175], 0
	v_mfma_f32_16x16x32_bf16 v[124:127], v[132:135], v[172:175], 0
	v_mfma_f32_16x16x32_bf16 v[104:107], v[112:115], v[180:183], 0
	v_mfma_f32_16x16x32_bf16 v[96:99], v[132:135], v[180:183], 0
	v_mfma_f32_16x16x32_bf16 v[76:79], v[112:115], v[188:191], 0
	v_mfma_f32_16x16x32_bf16 v[72:75], v[132:135], v[188:191], 0
	v_mfma_f32_16x16x32_bf16 v[152:155], v[120:123], v[168:171], v[152:155]
	v_mfma_f32_16x16x32_bf16 v[148:151], v[144:147], v[168:171], v[148:151]
	v_mfma_f32_16x16x32_bf16 v[128:131], v[120:123], v[176:179], v[128:131]
	v_mfma_f32_16x16x32_bf16 v[124:127], v[144:147], v[176:179], v[124:127]
	v_mfma_f32_16x16x32_bf16 v[104:107], v[120:123], v[184:187], v[104:107]
	v_mfma_f32_16x16x32_bf16 v[96:99], v[144:147], v[184:187], v[96:99]
	v_mfma_f32_16x16x32_bf16 v[76:79], v[120:123], v[208:211], v[76:79]
	v_mfma_f32_16x16x32_bf16 v[72:75], v[144:147], v[208:211], v[72:75]
	s_setprio 0
	s_barrier
	v_lshl_add_u64 v[198:199], s[28:29], 0, v[192:193]
	s_add_i32 m0, s39, 0x10000
	ds_read_b128 v[156:159], v236 offset:16384
	ds_read_b128 v[168:171], v236 offset:17408
	ds_read_b128 v[172:175], v236 offset:18432
	ds_read_b128 v[176:179], v236 offset:19456
	ds_read_b128 v[180:183], v236 offset:20480
	ds_read_b128 v[184:187], v236 offset:21504
	ds_read_b128 v[188:191], v236 offset:22528
	ds_read_b128 v[208:211], v236 offset:23552
	global_load_lds_dwordx4 v[198:199], off
	s_add_i32 m0, s39, 0x12000
	s_add_u32 s26, s28, 0xb0000
	v_lshl_add_u64 v[212:213], s[28:29], 0, v[202:203]
	s_addc_u32 s27, s29, 0
	global_load_lds_dwordx4 v[212:213], off
	v_lshl_add_u64 v[214:215], s[26:27], 0, v[192:193]
	s_add_i32 m0, s39, 0x14000
	v_lshl_add_u64 v[216:217], s[30:31], 0, v[194:195]
	global_load_lds_dwordx4 v[214:215], off
	s_add_i32 m0, s39, 0x16000
	v_lshl_add_u64 v[214:215], s[26:27], 0, v[202:203]
	global_load_lds_dwordx4 v[214:215], off
	s_mov_b32 m0, s40
	v_lshl_add_u64 v[214:215], s[30:31], 0, v[0:1]
	global_load_lds_dwordx4 v[214:215], off
	s_mov_b32 m0, s41
	s_add_i32 s54, 0, 0x18000
	global_load_lds_dwordx4 v[216:217], off
	s_waitcnt vmcnt(8) lgkmcnt(0)
	s_barrier
	s_setprio 1
	v_mfma_f32_16x16x32_bf16 v[64:67], v[68:71], v[156:159], 0
	v_mfma_f32_16x16x32_bf16 v[60:63], v[92:95], v[156:159], 0
	v_mfma_f32_16x16x32_bf16 v[48:51], v[68:71], v[172:175], 0
	v_mfma_f32_16x16x32_bf16 v[44:47], v[92:95], v[172:175], 0
	v_mfma_f32_16x16x32_bf16 v[32:35], v[68:71], v[180:183], 0
	v_mfma_f32_16x16x32_bf16 v[28:31], v[92:95], v[180:183], 0
	v_mfma_f32_16x16x32_bf16 v[16:19], v[68:71], v[188:191], 0
	v_mfma_f32_16x16x32_bf16 v[12:15], v[92:95], v[188:191], 0
	v_mfma_f32_16x16x32_bf16 v[64:67], v[80:83], v[168:171], v[64:67]
	v_mfma_f32_16x16x32_bf16 v[60:63], v[100:103], v[168:171], v[60:63]
	v_mfma_f32_16x16x32_bf16 v[48:51], v[80:83], v[176:179], v[48:51]
	v_mfma_f32_16x16x32_bf16 v[44:47], v[100:103], v[176:179], v[44:47]
	v_mfma_f32_16x16x32_bf16 v[32:35], v[80:83], v[184:187], v[32:35]
	v_mfma_f32_16x16x32_bf16 v[28:31], v[100:103], v[184:187], v[28:31]
	v_mfma_f32_16x16x32_bf16 v[16:19], v[80:83], v[208:211], v[16:19]
	v_mfma_f32_16x16x32_bf16 v[12:15], v[100:103], v[208:211], v[12:15]
	s_setprio 0
	s_setprio 1
	v_mfma_f32_16x16x32_bf16 v[56:59], v[112:115], v[156:159], 0
	v_mfma_f32_16x16x32_bf16 v[52:55], v[132:135], v[156:159], 0
	v_mfma_f32_16x16x32_bf16 v[40:43], v[112:115], v[172:175], 0
	v_mfma_f32_16x16x32_bf16 v[36:39], v[132:135], v[172:175], 0
	v_mfma_f32_16x16x32_bf16 v[24:27], v[112:115], v[180:183], 0
	v_mfma_f32_16x16x32_bf16 v[20:23], v[132:135], v[180:183], 0
	v_mfma_f32_16x16x32_bf16 v[8:11], v[112:115], v[188:191], 0
	v_mfma_f32_16x16x32_bf16 v[4:7], v[132:135], v[188:191], 0
	v_mfma_f32_16x16x32_bf16 v[56:59], v[120:123], v[168:171], v[56:59]
	v_mfma_f32_16x16x32_bf16 v[52:55], v[144:147], v[168:171], v[52:55]
	v_mfma_f32_16x16x32_bf16 v[40:43], v[120:123], v[176:179], v[40:43]
	v_mfma_f32_16x16x32_bf16 v[36:39], v[144:147], v[176:179], v[36:39]
	v_mfma_f32_16x16x32_bf16 v[24:27], v[120:123], v[184:187], v[24:27]
	v_mfma_f32_16x16x32_bf16 v[20:23], v[144:147], v[184:187], v[20:23]
	v_mfma_f32_16x16x32_bf16 v[8:11], v[120:123], v[208:211], v[8:11]
	v_mfma_f32_16x16x32_bf16 v[4:7], v[144:147], v[208:211], v[4:7]
	s_setprio 0
	s_barrier
	s_branch .Lkmid_3

; #define PG8_STAGE(bufoff, gbase, voff) do { _Pragma("unroll") for (int _i = 0; _i < 2; ++_i) \
;         __builtin_amdgcn_global_load_lds((const unsigned*)((const char*)(gbase) + (voff)[_i]), (PG8_LAS unsigned*)(lds + (bufoff) + ldsw + _i * 8192), 16, 0, 0); } while (0)
; #define PG8_LDA(dst, b, h) do { _Pragma("unroll") for (int m = 0; m < 4; ++m) _Pragma("unroll") for (int k = 0; k < 2; ++k) dst[m][k] = *(const PG8_LAS bf16x8*)(lds + PG8_SA(b, h) + aoff + m * 2048 + k * 1024); } while (0)
; #define PG8_LDB(dst, b, h) do { _Pragma("unroll") for (int n = 0; n < 2; ++n) _Pragma("unroll") for (int k = 0; k < 2; ++k) dst[n][k] = *(const PG8_LAS bf16x8*)(lds + PG8_SB(b, h) + boff + n * 2048 + k * 1024); } while (0)
; #define PG8_MMA(ai, bj, At, Bt) do { __builtin_amdgcn_s_setprio(1); _Pragma("unroll") for (int m = 0; m < 4; ++m) _Pragma("unroll") for (int n = 0; n < 2; ++n) _Pragma("unroll") for (int k = 0; k < 2; ++k) \
;         acc[ai][bj][m][n] = __builtin_amdgcn_mfma_f32_16x16x32_bf16(Bt[n][k], At[m][k], acc[ai][bj][m][n], 0, 0, 0); __builtin_amdgcn_s_setprio(0); } while (0)
; #define PG8_WAIT_V(n) asm volatile("s_waitcnt vmcnt(" #n ")" ::: "memory")
; #define PG8_WAIT_L(n) asm volatile("s_waitcnt lgkmcnt(" #n ")" ::: "memory")
; #define PG8_BAR __builtin_amdgcn_s_barrier()
; #define PG8_SCHED __builtin_amdgcn_sched_barrier(0)
; template <class Epi, class Sched, bool ALIGN_EPI = false, bool SP2 = false>
; __device__ __forceinline__ void gemm_phase(PG8_LAS unsigned char* lds, const Gemm g, const Sched& S, const Epi& E) {
;     ...
;             PG8_LDB(B0, 1, 0); PG8_LDB(B1, 1, 1); PG8_SCHED; PG8_LDA(At, 1, 0); PG8_STAGE(PG8_SA(0, 1), a2 + hstep, voffA);
;             PG8_WAIT_V(8); PG8_WAIT_L(0); PG8_BAR; PG8_MMA(0, 0, At, B0); PG8_MMA(0, 1, At, B1); PG8_BAR; PG8_SCHED;
;             PG8_LDA(At, 1, 1); PG8_STAGE(PG8_SB(1, 0), b3, voffB); PG8_STAGE(PG8_SB(1, 1), b3 + hstep, voffB); PG8_STAGE(PG8_SA(1, 0), a3, voffA);
;             PG8_WAIT_V(8); PG8_WAIT_L(0); PG8_BAR; PG8_MMA(1, 0, At, B0); PG8_MMA(1, 1, At, B1); PG8_BAR; PG8_SCHED;
.Lkmid_3:
	ds_read_b128 v[68:71], v234 offset:32768
	ds_read_b128 v[80:83], v234 offset:33792
	ds_read_b128 v[92:95], v234 offset:34816
	ds_read_b128 v[100:103], v234 offset:35840
	ds_read_b128 v[112:115], v234 offset:49152
	ds_read_b128 v[120:123], v234 offset:50176
	ds_read_b128 v[132:135], v234 offset:51200
	ds_read_b128 v[144:147], v234 offset:52224
	s_add_u32 s26, s30, 0xb0000
	s_addc_u32 s27, s31, 0
	s_mov_b32 m0, s42
	v_lshl_add_u64 v[218:219], s[26:27], 0, v[0:1]
	ds_read_b128 v[156:159], v236 offset:32768
	ds_read_b128 v[168:171], v236 offset:33792
	ds_read_b128 v[172:175], v236 offset:34816
	ds_read_b128 v[176:179], v236 offset:35840
	ds_read_b128 v[180:183], v236 offset:36864
	ds_read_b128 v[184:187], v236 offset:37888
	ds_read_b128 v[188:191], v236 offset:38912
	ds_read_b128 v[208:211], v236 offset:39936
	global_load_lds_dwordx4 v[218:219], off
	s_mov_b32 m0, s43
	v_lshl_add_u64 v[218:219], s[26:27], 0, v[194:195]
	global_load_lds_dwordx4 v[218:219], off
	s_waitcnt vmcnt(8) lgkmcnt(0)
	s_barrier
	s_setprio 1
	v_mfma_f32_16x16x32_bf16 v[164:167], v[68:71], v[156:159], v[164:167]
	v_mfma_f32_16x16x32_bf16 v[160:163], v[92:95], v[156:159], v[160:163]
	v_mfma_f32_16x16x32_bf16 v[140:143], v[68:71], v[172:175], v[140:143]
	v_mfma_f32_16x16x32_bf16 v[136:139], v[92:95], v[172:175], v[136:139]
	v_mfma_f32_16x16x32_bf16 v[116:119], v[68:71], v[180:183], v[116:119]
	v_mfma_f32_16x16x32_bf16 v[108:111], v[92:95], v[180:183], v[108:111]
	v_mfma_f32_16x16x32_bf16 v[88:91], v[68:71], v[188:191], v[88:91]
	v_mfma_f32_16x16x32_bf16 v[84:87], v[92:95], v[188:191], v[84:87]
	v_mfma_f32_16x16x32_bf16 v[164:167], v[80:83], v[168:171], v[164:167]
	v_mfma_f32_16x16x32_bf16 v[160:163], v[100:103], v[168:171], v[160:163]
	v_mfma_f32_16x16x32_bf16 v[140:143], v[80:83], v[176:179], v[140:143]
	v_mfma_f32_16x16x32_bf16 v[136:139], v[100:103], v[176:179], v[136:139]
	v_mfma_f32_16x16x32_bf16 v[116:119], v[80:83], v[184:187], v[116:119]
	v_mfma_f32_16x16x32_bf16 v[108:111], v[100:103], v[184:187], v[108:111]
	v_mfma_f32_16x16x32_bf16 v[88:91], v[80:83], v[208:211], v[88:91]
	v_mfma_f32_16x16x32_bf16 v[84:87], v[100:103], v[208:211], v[84:87]
	s_setprio 0
	s_setprio 1
	v_mfma_f32_16x16x32_bf16 v[152:155], v[112:115], v[156:159], v[152:155]
	v_mfma_f32_16x16x32_bf16 v[148:151], v[132:135], v[156:159], v[148:151]
	v_mfma_f32_16x16x32_bf16 v[128:131], v[112:115], v[172:175], v[128:131]
	v_mfma_f32_16x16x32_bf16 v[124:127], v[132:135], v[172:175], v[124:127]
	v_mfma_f32_16x16x32_bf16 v[104:107], v[112:115], v[180:183], v[104:107]
	v_mfma_f32_16x16x32_bf16 v[96:99], v[132:135], v[180:183], v[96:99]
	v_mfma_f32_16x16x32_bf16 v[76:79], v[112:115], v[188:191], v[76:79]
	v_mfma_f32_16x16x32_bf16 v[72:75], v[132:135], v[188:191], v[72:75]
	v_mfma_f32_16x16x32_bf16 v[152:155], v[120:123], v[168:171], v[152:155]
	v_mfma_f32_16x16x32_bf16 v[148:151], v[144:147], v[168:171], v[148:151]
	v_mfma_f32_16x16x32_bf16 v[128:131], v[120:123], v[176:179], v[128:131]
	v_mfma_f32_16x16x32_bf16 v[124:127], v[144:147], v[176:179], v[124:127]
	v_mfma_f32_16x16x32_bf16 v[104:107], v[120:123], v[184:187], v[104:107]
	v_mfma_f32_16x16x32_bf16 v[96:99], v[144:147], v[184:187], v[96:99]
	v_mfma_f32_16x16x32_bf16 v[76:79], v[120:123], v[208:211], v[76:79]
	v_mfma_f32_16x16x32_bf16 v[72:75], v[144:147], v[208:211], v[72:75]
	s_setprio 0
	s_barrier
	s_add_i32 m0, s39, 0x17f80
	ds_read_b128 v[156:159], v236 offset:49152
	ds_read_b128 v[168:171], v236 offset:50176
	ds_read_b128 v[172:175], v236 offset:51200
	ds_read_b128 v[176:179], v236 offset:52224
	ds_read_b128 v[180:183], v236 offset:53248
	ds_read_b128 v[184:187], v236 offset:54272
	ds_read_b128 v[188:191], v236 offset:55296
	ds_read_b128 v[208:211], v236 offset:56320
	global_load_lds_dwordx4 v[198:199], off offset:128
	s_add_i32 m0, s39, 0x19f80
	s_add_u32 s26, s28, 0xb0080
	s_addc_u32 s27, s29, 0
	global_load_lds_dwordx4 v[212:213], off offset:128
	s_add_i32 m0, s39, 0x1c000
	v_lshl_add_u64 v[198:199], s[26:27], 0, v[192:193]
	global_load_lds_dwordx4 v[198:199], off
	s_add_i32 m0, s39, 0x1e000
	v_lshl_add_u64 v[198:199], s[26:27], 0, v[202:203]
	global_load_lds_dwordx4 v[198:199], off
	s_add_i32 m0, s47, 0xffffff80
	s_add_u32 s44, s44, 0x100
	s_addc_u32 s45, s45, 0
	global_load_lds_dwordx4 v[214:215], off offset:128
	s_add_i32 m0, s48, 0xffffff80
	s_mov_b64 s[26:27], s[8:9]
	global_load_lds_dwordx4 v[216:217], off offset:128
	s_waitcnt vmcnt(8) lgkmcnt(0)
	s_barrier
	s_setprio 1
	v_mfma_f32_16x16x32_bf16 v[64:67], v[68:71], v[156:159], v[64:67]
	v_mfma_f32_16x16x32_bf16 v[60:63], v[92:95], v[156:159], v[60:63]
	v_mfma_f32_16x16x32_bf16 v[48:51], v[68:71], v[172:175], v[48:51]
	v_mfma_f32_16x16x32_bf16 v[44:47], v[92:95], v[172:175], v[44:47]
	v_mfma_f32_16x16x32_bf16 v[32:35], v[68:71], v[180:183], v[32:35]
	v_mfma_f32_16x16x32_bf16 v[28:31], v[92:95], v[180:183], v[28:31]
	v_mfma_f32_16x16x32_bf16 v[16:19], v[68:71], v[188:191], v[16:19]
	v_mfma_f32_16x16x32_bf16 v[12:15], v[92:95], v[188:191], v[12:15]
	v_mfma_f32_16x16x32_bf16 v[64:67], v[80:83], v[168:171], v[64:67]
	v_mfma_f32_16x16x32_bf16 v[60:63], v[100:103], v[168:171], v[60:63]
	v_mfma_f32_16x16x32_bf16 v[48:51], v[80:83], v[176:179], v[48:51]
	v_mfma_f32_16x16x32_bf16 v[44:47], v[100:103], v[176:179], v[44:47]
	v_mfma_f32_16x16x32_bf16 v[32:35], v[80:83], v[184:187], v[32:35]
	v_mfma_f32_16x16x32_bf16 v[28:31], v[100:103], v[184:187], v[28:31]
	v_mfma_f32_16x16x32_bf16 v[16:19], v[80:83], v[208:211], v[16:19]
	v_mfma_f32_16x16x32_bf16 v[12:15], v[100:103], v[208:211], v[12:15]
	s_setprio 0
	s_setprio 1
	v_mfma_f32_16x16x32_bf16 v[56:59], v[112:115], v[156:159], v[56:59]
	v_mfma_f32_16x16x32_bf16 v[52:55], v[132:135], v[156:159], v[52:55]
	v_mfma_f32_16x16x32_bf16 v[40:43], v[112:115], v[172:175], v[40:43]
	v_mfma_f32_16x16x32_bf16 v[36:39], v[132:135], v[172:175], v[36:39]
	v_mfma_f32_16x16x32_bf16 v[24:27], v[112:115], v[180:183], v[24:27]
	v_mfma_f32_16x16x32_bf16 v[20:23], v[132:135], v[180:183], v[20:23]
	v_mfma_f32_16x16x32_bf16 v[8:11], v[112:115], v[188:191], v[8:11]
	v_mfma_f32_16x16x32_bf16 v[4:7], v[132:135], v[188:191], v[4:7]
	v_mfma_f32_16x16x32_bf16 v[56:59], v[120:123], v[168:171], v[56:59]
	v_mfma_f32_16x16x32_bf16 v[52:55], v[144:147], v[168:171], v[52:55]
	v_mfma_f32_16x16x32_bf16 v[40:43], v[120:123], v[176:179], v[40:43]
	v_mfma_f32_16x16x32_bf16 v[36:39], v[144:147], v[176:179], v[36:39]
	v_mfma_f32_16x16x32_bf16 v[24:27], v[120:123], v[184:187], v[24:27]
	v_mfma_f32_16x16x32_bf16 v[20:23], v[144:147], v[184:187], v[20:23]
	v_mfma_f32_16x16x32_bf16 v[8:11], v[120:123], v[208:211], v[8:11]
	v_mfma_f32_16x16x32_bf16 v[4:7], v[144:147], v[208:211], v[4:7]
	s_setprio 0
	s_barrier
	s_add_i32 s53, s53, 2
	s_cmp_gt_u32 s53, 41
	s_cbranch_scc0 .LBB0_480
	s_and_b64 vcc, exec, s[20:21]
	s_cbranch_vccz .LBB0_483
	s_barrier
